# pc_phase item prologue: per-load 64-bit address arithmetic replaced by running row pointers (same 91 loads), SV store base hoisted out of the 15 t-blocks (-245 instrs per item)
# speedup vs baseline: 1.0015x; 1.0015x over previous
; __device__ __forceinline__ void pc_phase(LAS unsigned char* lds, const bf16* Pp_, const bf16* LO, const float* mu, const float* w0, const float* a0, const float* k_k, const float* k_a, const float* r_k, ...
;     ...
;         unsigned short sr_[17], sk_[17], sv_[17], slw[16], sla[16];
;         { const bf16* pp = Pp_ + (size_t)(c > 0 ? m0 - 1 : m0) * EV_IN_P + 3072 + ch; sr_[0] = pp[0]; sk_[0] = pp[1024]; sv_[0] = pp[2048]; }
; #pragma unroll
;         for (int t = 0; t < 16; ++t) { const bf16* pr = Pp_ + (size_t)(m0 + t) * EV_IN_P + 3072 + ch; sr_[t + 1] = pr[0]; sk_[t + 1] = pr[1024]; sv_[t + 1] = pr[2048];
;             const bf16* lo = LO + (size_t)(m0 + t) * LORA_N + ch; slw[t] = lo[0]; sla[t] = lo[1024]; }
.LBB0_281:
	s_bfe_u32 s1, s11, 0x40008
	v_lshl_or_b32 v152, s1, 6, v185
	s_and_b32 s1, s11, 0xff
	s_and_b32 s0, s11, 0xfffff000
	s_lshl_b32 s1, s1, 4
	s_or_b32 s0, s0, s1
	v_lshlrev_b32_e32 v154, 2, v152
	v_lshlrev_b32_e32 v152, 1, v152
	v_mov_b32_e32 v153, 0
	v_mov_b32_e32 v155, 0
	v_readlane_b32 vcc_lo, v255, 13
	v_readlane_b32 vcc_hi, v255, 14
	s_nop 1
	s_add_u32 vcc_lo, vcc_lo, 0x1000
	s_addc_u32 vcc_hi, vcc_hi, 0
	v_lshl_add_u64 v[150:151], vcc, 0, v[154:155]
	global_load_dword v10, v[150:151], off offset:-4096
	global_load_dword v9, v[150:151], off
	s_add_u32 vcc_lo, vcc_lo, 0x1000
	s_addc_u32 vcc_hi, vcc_hi, 0
	v_lshl_add_u64 v[150:151], vcc, 0, v[154:155]
	global_load_dword v12, v[150:151], off
	v_readlane_b32 vcc_lo, v255, 15
	v_readlane_b32 vcc_hi, v255, 16
	s_nop 1
	v_lshl_add_u64 v[150:151], vcc, 0, v[154:155]
	global_load_dword v8, v[150:151], off
	v_readlane_b32 vcc_lo, v255, 20
	v_readlane_b32 vcc_hi, v255, 21
	s_nop 1
	v_lshl_add_u64 v[150:151], vcc, 0, v[154:155]
	global_load_dword v15, v[150:151], off
	v_readlane_b32 vcc_lo, v255, 22
	v_readlane_b32 vcc_hi, v255, 23
	s_nop 1
	v_lshl_add_u64 v[150:151], vcc, 0, v[154:155]
	global_load_dword v14, v[150:151], off
	v_readlane_b32 vcc_lo, v255, 24
	v_readlane_b32 vcc_hi, v255, 25
	s_nop 1
	v_lshl_add_u64 v[150:151], vcc, 0, v[154:155]
	global_load_dword v13, v[150:151], off
	v_readlane_b32 vcc_lo, v255, 26
	v_readlane_b32 vcc_hi, v255, 27
	s_nop 1
	v_lshl_add_u64 v[150:151], vcc, 0, v[154:155]
	global_load_dword v11, v[150:151], off
	v_readlane_b32 vcc_lo, v254, 63
	v_readlane_b32 vcc_hi, v255, 0
	s_mul_i32 s1, s0, 0x3400
	s_add_u32 vcc_lo, vcc_lo, s1
	s_addc_u32 vcc_hi, vcc_hi, 0
	s_add_u32 vcc_lo, vcc_lo, 0x2000
	s_addc_u32 vcc_hi, vcc_hi, 0
	v_lshl_add_u64 v[146:147], vcc, 0, v[152:153]
	s_and_b32 s1, s0, 0xff0
	s_cmp_eq_u32 s1, 0
	s_cselect_b32 s1, 0, 0x3400
	s_sub_u32 vcc_lo, vcc_lo, s1
	s_subb_u32 vcc_hi, vcc_hi, 0
	v_lshl_add_u64 v[150:151], vcc, 0, v[152:153]
	global_load_ushort v134, v[150:151], off offset:-2048
	global_load_ushort v135, v[150:151], off
	global_load_ushort v138, v[150:151], off offset:2048
	v_readlane_b32 vcc_lo, v255, 1
	v_readlane_b32 vcc_hi, v255, 2
	s_mul_i32 s1, s0, 0x1800
	s_add_u32 vcc_lo, vcc_lo, s1
	s_addc_u32 vcc_hi, vcc_hi, 0
	v_lshl_add_u64 v[148:149], vcc, 0, v[152:153]
	global_load_ushort v132, v[148:149], off
	global_load_ushort v136, v[146:147], off offset:-2048
	global_load_ushort v137, v[146:147], off
	global_load_ushort v139, v[146:147], off offset:2048
	global_load_ushort v133, v[148:149], off offset:2048
	s_movk_i32 s0, 0x3400
	s_mov_b32 s1, 0
	v_lshl_add_u64 v[146:147], v[146:147], 0, s[0:1]
	s_movk_i32 s0, 0x1800
	v_lshl_add_u64 v[148:149], v[148:149], 0, s[0:1]
	global_load_ushort v129, v[146:147], off offset:-2048
	global_load_ushort v130, v[146:147], off
	global_load_ushort v131, v[146:147], off offset:2048
	global_load_ushort v127, v[148:149], off
	global_load_ushort v128, v[148:149], off offset:2048
	s_movk_i32 s0, 0x3400
	s_mov_b32 s1, 0
	v_lshl_add_u64 v[146:147], v[146:147], 0, s[0:1]
	s_movk_i32 s0, 0x1800
	v_lshl_add_u64 v[148:149], v[148:149], 0, s[0:1]
	global_load_ushort v124, v[146:147], off offset:-2048
	global_load_ushort v125, v[146:147], off
	global_load_ushort v126, v[146:147], off offset:2048
	global_load_ushort v122, v[148:149], off
	global_load_ushort v123, v[148:149], off offset:2048
	s_movk_i32 s0, 0x3400
	s_mov_b32 s1, 0
	v_lshl_add_u64 v[146:147], v[146:147], 0, s[0:1]
	s_movk_i32 s0, 0x1800
	v_lshl_add_u64 v[148:149], v[148:149], 0, s[0:1]
	global_load_ushort v119, v[146:147], off offset:-2048
	global_load_ushort v120, v[146:147], off
	global_load_ushort v121, v[146:147], off offset:2048
	global_load_ushort v117, v[148:149], off
	global_load_ushort v118, v[148:149], off offset:2048
	s_movk_i32 s0, 0x3400
	s_mov_b32 s1, 0
	v_lshl_add_u64 v[146:147], v[146:147], 0, s[0:1]
	s_movk_i32 s0, 0x1800
	v_lshl_add_u64 v[148:149], v[148:149], 0, s[0:1]
	global_load_ushort v114, v[146:147], off offset:-2048
	global_load_ushort v115, v[146:147], off
	global_load_ushort v116, v[146:147], off offset:2048
	global_load_ushort v112, v[148:149], off
	global_load_ushort v113, v[148:149], off offset:2048
	s_movk_i32 s0, 0x3400
	s_mov_b32 s1, 0
	v_lshl_add_u64 v[146:147], v[146:147], 0, s[0:1]
	s_movk_i32 s0, 0x1800
	v_lshl_add_u64 v[148:149], v[148:149], 0, s[0:1]
	global_load_ushort v109, v[146:147], off offset:-2048
	global_load_ushort v110, v[146:147], off
	global_load_ushort v111, v[146:147], off offset:2048
	global_load_ushort v107, v[148:149], off
	global_load_ushort v108, v[148:149], off offset:2048
	s_movk_i32 s0, 0x3400
	s_mov_b32 s1, 0
	v_lshl_add_u64 v[146:147], v[146:147], 0, s[0:1]
	s_movk_i32 s0, 0x1800
	v_lshl_add_u64 v[148:149], v[148:149], 0, s[0:1]
	global_load_ushort v104, v[146:147], off offset:-2048
	global_load_ushort v105, v[146:147], off
	global_load_ushort v106, v[146:147], off offset:2048
	global_load_ushort v102, v[148:149], off
	global_load_ushort v103, v[148:149], off offset:2048
	s_movk_i32 s0, 0x3400
	s_mov_b32 s1, 0
	v_lshl_add_u64 v[146:147], v[146:147], 0, s[0:1]
	s_movk_i32 s0, 0x1800
	v_lshl_add_u64 v[148:149], v[148:149], 0, s[0:1]
	global_load_ushort v99, v[146:147], off offset:-2048
	global_load_ushort v100, v[146:147], off
	global_load_ushort v101, v[146:147], off offset:2048
	global_load_ushort v95, v[148:149], off
	global_load_ushort v98, v[148:149], off offset:2048
	s_movk_i32 s0, 0x3400
	s_mov_b32 s1, 0
	v_lshl_add_u64 v[146:147], v[146:147], 0, s[0:1]
	s_movk_i32 s0, 0x1800
	v_lshl_add_u64 v[148:149], v[148:149], 0, s[0:1]
	global_load_ushort v92, v[146:147], off offset:-2048
; __device__ __forceinline__ float bf2f(bf16 b) { return __uint_as_float((unsigned)b << 16); }
; __device__ __forceinline__ bf16 f2bf(float f) { return (bf16)(pk_bf16(f, 0.f) & 0xffffu); }
; __device__ __forceinline__ float fexp(float x) { return __builtin_amdgcn_exp2f(x * 1.4426950408889634f); }
; __device__ __forceinline__ float flog(float x) { return __builtin_amdgcn_logf(x) * 0.6931471805599453f; }
; __device__ __forceinline__ float fsigmoid(float x) { return __builtin_amdgcn_rcpf(1.0f + fexp(-x)); }
; __device__ __forceinline__ void pc_phase(LAS unsigned char* lds, const bf16* Pp_, const bf16* LO, const float* mu, const float* w0, const float* a0, const float* k_k, const float* k_a, const float* r_k, ...
;     ...
;         for (int t = 0; t < 16; ++t) { const bf16* pr = Pp_ + (size_t)(m0 + t) * EV_IN_P + 3072 + ch; sr_[t + 1] = pr[0]; sk_[t + 1] = pr[1024]; sv_[t + 1] = pr[2048];
;             const bf16* lo = LO + (size_t)(m0 + t) * LORA_N + ch; slw[t] = lo[0]; sla[t] = lo[1024]; }
;         const float z1 = (c > 0) ? 1.0f : 0.0f;
;         float P = 1.0f, r1 = bf2f(sr_[0]) * z1, k1 = bf2f(sk_[0]) * z1, v1 = bf2f(sv_[0]) * z1;
; #pragma unroll
;         for (int t = 0; t < 16; ++t) {
;             const float r0 = bf2f(sr_[t + 1]), k0 = bf2f(sk_[t + 1]), v0 = bf2f(sv_[t + 1]);
;             const float r = r0 + (r1 - r0) * mu_r, k = k0 + (k1 - k0) * mu_k, v = v0 + (v1 - v0) * mu_v; r1 = r0; k1 = k0; v1 = v0;
;             const float z = -(w0c + bf2f(slw[t])); const float sp = fmaxf(z, 0.f) + flog(1.0f + fexp(-fabsf(z))); const float w = -sp - 0.5f;
;             const float dec = fexp(-fexp(w)); const float a = fsigmoid(a0c + bf2f(sla[t]));
;             float kk = k * kkc; const float n2 = wsum_dpp(kk * kk); kk = kk / fmaxf(sqrtf(n2), 1e-12f);
;             const float kp = bf2f(f2bf(k * (1.0f + (a - 1.0f) * kac))), bb = bf2f(f2bf(kk * a)), rr = bf2f(f2bf(r)); kk = bf2f(f2bf(kk));
;             const float coef = wsum_dpp(rr * kp * rkc);
;             SV[(ib + t) * 64 + lane] = f2bf(v);
;             if (lane == 0) COEF[(size_t)(m0 + t) * 16 + h] = coef;
;             const float Pp = P; P *= dec; const float inv = 1.0f / P;
;             XKK[t * 72 + lane] = f2bf(kk * Pp); XR[t * 72 + lane] = f2bf(rr * P); XK[t * 72 + lane] = f2bf(kp * inv); XB[t * 72 + lane] = f2bf(bb * inv); }
	global_load_ushort v93, v[146:147], off
	global_load_ushort v94, v[146:147], off offset:2048
	global_load_ushort v90, v[148:149], off
	global_load_ushort v91, v[148:149], off offset:2048
	s_movk_i32 s0, 0x3400
	s_mov_b32 s1, 0
	v_lshl_add_u64 v[146:147], v[146:147], 0, s[0:1]
	s_movk_i32 s0, 0x1800
	v_lshl_add_u64 v[148:149], v[148:149], 0, s[0:1]
	global_load_ushort v87, v[146:147], off offset:-2048
	global_load_ushort v88, v[146:147], off
	global_load_ushort v89, v[146:147], off offset:2048
	global_load_ushort v85, v[148:149], off
	global_load_ushort v86, v[148:149], off offset:2048
	s_movk_i32 s0, 0x3400
	s_mov_b32 s1, 0
	v_lshl_add_u64 v[146:147], v[146:147], 0, s[0:1]
	s_movk_i32 s0, 0x1800
	v_lshl_add_u64 v[148:149], v[148:149], 0, s[0:1]
	global_load_ushort v82, v[146:147], off offset:-2048
	global_load_ushort v83, v[146:147], off
	global_load_ushort v84, v[146:147], off offset:2048
	global_load_ushort v80, v[148:149], off
	global_load_ushort v81, v[148:149], off offset:2048
	s_movk_i32 s0, 0x3400
	s_mov_b32 s1, 0
	v_lshl_add_u64 v[146:147], v[146:147], 0, s[0:1]
	s_movk_i32 s0, 0x1800
	v_lshl_add_u64 v[148:149], v[148:149], 0, s[0:1]
	global_load_ushort v77, v[146:147], off offset:-2048
	global_load_ushort v78, v[146:147], off
	global_load_ushort v79, v[146:147], off offset:2048
	global_load_ushort v75, v[148:149], off
	global_load_ushort v76, v[148:149], off offset:2048
	s_movk_i32 s0, 0x3400
	s_mov_b32 s1, 0
	v_lshl_add_u64 v[146:147], v[146:147], 0, s[0:1]
	s_movk_i32 s0, 0x1800
	v_lshl_add_u64 v[148:149], v[148:149], 0, s[0:1]
	global_load_ushort v72, v[146:147], off offset:-2048
	global_load_ushort v73, v[146:147], off
	global_load_ushort v74, v[146:147], off offset:2048
	global_load_ushort v70, v[148:149], off
	global_load_ushort v71, v[148:149], off offset:2048
	s_movk_i32 s0, 0x3400
	s_mov_b32 s1, 0
	v_lshl_add_u64 v[146:147], v[146:147], 0, s[0:1]
	s_movk_i32 s0, 0x1800
	v_lshl_add_u64 v[148:149], v[148:149], 0, s[0:1]
	global_load_ushort v66, v[146:147], off offset:-2048
	global_load_ushort v67, v[146:147], off
	global_load_ushort v68, v[146:147], off offset:2048
	global_load_ushort v65, v[148:149], off
	global_load_ushort v69, v[148:149], off offset:2048
	s_movk_i32 s0, 0x3400
	s_mov_b32 s1, 0
	v_lshl_add_u64 v[146:147], v[146:147], 0, s[0:1]
	s_movk_i32 s0, 0x1800
	v_lshl_add_u64 v[148:149], v[148:149], 0, s[0:1]
	global_load_ushort v62, v[146:147], off offset:-2048
	global_load_ushort v63, v[146:147], off
	global_load_ushort v64, v[146:147], off offset:2048
	global_load_ushort v21, v[148:149], off
	global_load_ushort v61, v[148:149], off offset:2048
	s_movk_i32 s0, 0x3400
	s_mov_b32 s1, 0
	v_lshl_add_u64 v[146:147], v[146:147], 0, s[0:1]
	s_movk_i32 s0, 0x1800
	v_lshl_add_u64 v[148:149], v[148:149], 0, s[0:1]
	global_load_ushort v18, v[146:147], off offset:-2048
	global_load_ushort v19, v[146:147], off
	global_load_ushort v20, v[146:147], off offset:2048
	global_load_ushort v16, v[148:149], off
	global_load_ushort v17, v[148:149], off offset:2048
	s_and_b32 s1, s11, 0xff
	s_bfe_u32 s0, s11, 0x40008
	s_and_b32 s2, s11, 0xfffff000
	s_lshl_b32 s4, s1, 4
	s_or_b32 s56, s4, s2
	s_cmp_eq_u32 s1, 0
	s_cselect_b64 s[94:95], -1, 0
	s_or_b32 s86, s56, 1
	s_or_b32 s34, s56, 2
	s_or_b32 s40, s56, 3
	s_or_b32 s72, s56, 4
	s_or_b32 s68, s56, 5
	s_or_b32 s66, s56, 6
	s_or_b32 s64, s56, 7
	s_or_b32 s62, s56, 8
	s_or_b32 s36, s56, 9
	s_or_b32 s84, s56, 10
	s_or_b32 s82, s56, 11
	s_or_b32 s80, s56, 12
	s_or_b32 s78, s56, 13
	s_or_b32 s76, s56, 14
	s_or_b32 s74, s56, 15
	v_cndmask_b32_e64 v96, 1.0, 0, s[94:95]
	s_lshl_b32 s0, s0, 2
	v_lshl_add_u64 v[6:7], s[88:89], 0, v[4:5]
	s_add_u32 s2, s49, s0
	s_addc_u32 s14, s35, 0
	v_add_co_u32_e32 v156, vcc, 0x33600000, v6
	s_nop 1
	v_addc_co_u32_e32 v157, vcc, 0, v7, vcc
	s_waitcnt vmcnt(0) lgkmcnt(0)
	v_lshlrev_b32_e32 v140, 16, v134
	v_lshlrev_b32_e32 v141, 16, v135
	v_lshlrev_b32_e32 v138, 16, v138
	v_lshlrev_b32_e32 v136, 16, v136
	v_lshlrev_b32_e32 v135, 16, v137
	v_fma_f32 v137, v96, v140, -v136
	v_fma_f32 v137, v10, v137, v136
	v_cvt_pk_bf16_f32 v137, v137, s0
	v_lshlrev_b32_e32 v137, 16, v137
	v_lshlrev_b32_e32 v134, 16, v139
	v_fma_f32 v139, v96, v141, -v135
	v_lshlrev_b32_e32 v133, 16, v133
	v_add_f32_e32 v133, v15, v133
	v_mul_f32_e32 v133, 0xbfb8aa3b, v133
	v_exp_f32_e32 v133, v133
	v_fma_f32 v140, v9, v139, v135
	v_mul_f32_e32 v139, v14, v140
	v_fma_f32 v96, v96, v138, -v134
	v_add_f32_e32 v133, 1.0, v133
	v_rcp_f32_e32 v138, v133
	v_mul_f32_e32 v133, v139, v139
	v_fma_f32 v96, v12, v96, v134
	s_nop 0
	v_mov_b32_dpp v133, v133 quad_perm:[1,0,3,2] row_mask:0xf bank_mask:0xf bound_ctrl:1
	v_fmac_f32_e32 v133, v139, v139
	s_nop 1
	v_add_f32_dpp v133, v133, v133 quad_perm:[2,3,0,1] row_mask:0xf bank_mask:0xf bound_ctrl:1
	s_nop 1
	v_add_f32_dpp v133, v133, v133 row_ror:4 row_mask:0xf bank_mask:0xf bound_ctrl:1
	s_nop 1
	v_add_f32_dpp v133, v133, v133 row_ror:8 row_mask:0xf bank_mask:0xf bound_ctrl:1
	s_nop 0
	v_readlane_b32 s7, v133, 0
	v_readlane_b32 s8, v133, 16
	v_readlane_b32 s6, v133, 32
	v_readlane_b32 s9, v133, 48
	v_add_f32_e32 v133, -1.0, v138
	v_fma_f32 v133, v13, v133, 1.0
	v_mul_f32_e32 v133, v140, v133
	v_cvt_pk_bf16_f32 v133, v133, s0
	v_lshlrev_b32_e32 v133, 16, v133
	v_mul_f32_e32 v140, v137, v133
	v_mul_f32_e32 v141, v11, v140
	s_nop 1
	v_mov_b32_dpp v141, v141 quad_perm:[1,0,3,2] row_mask:0xf bank_mask:0xf bound_ctrl:1
	v_fmac_f32_e32 v141, v11, v140
	s_nop 1
	v_add_f32_dpp v140, v141, v141 quad_perm:[2,3,0,1] row_mask:0xf bank_mask:0xf bound_ctrl:1
	s_nop 1
	v_add_f32_dpp v140, v140, v140 row_ror:4 row_mask:0xf bank_mask:0xf bound_ctrl:1
	s_nop 1
	v_add_f32_dpp v140, v140, v140 row_ror:8 row_mask:0xf bank_mask:0xf bound_ctrl:1
	s_nop 0
	v_readlane_b32 s0, v140, 0
	v_readlane_b32 s15, v140, 16
	v_readlane_b32 s1, v140, 32
	v_readlane_b32 s17, v140, 48
	v_cvt_pk_bf16_f32 v96, v96, s0
	global_store_short v[156:157], v96, off
	s_and_saveexec_b64 s[4:5], s[38:39]
	s_cbranch_execz .LBB0_283
	s_ashr_i32 s57, s56, 31
	s_lshl_b64 s[30:31], s[56:57], 6
	s_add_u32 s30, s2, s30
	v_mov_b32_e32 v140, s15
	v_mov_b32_e32 v141, s17
	s_addc_u32 s31, s14, s31
	v_pk_add_f32 v[140:141], s[0:1], v[140:141]
	s_nop 0
	v_add_f32_e32 v96, v140, v141
	v_mov_b64_e32 v[140:141], s[30:31]
	global_store_dword v[140:141], v96, off
; __device__ __forceinline__ float bf2f(bf16 b) { return __uint_as_float((unsigned)b << 16); }
; __device__ __forceinline__ bf16 f2bf(float f) { return (bf16)(pk_bf16(f, 0.f) & 0xffffu); }
; __device__ __forceinline__ float fexp(float x) { return __builtin_amdgcn_exp2f(x * 1.4426950408889634f); }
; __device__ __forceinline__ float flog(float x) { return __builtin_amdgcn_logf(x) * 0.6931471805599453f; }
; __device__ __forceinline__ float fsigmoid(float x) { return __builtin_amdgcn_rcpf(1.0f + fexp(-x)); }
; __device__ __forceinline__ void pc_phase(LAS unsigned char* lds, const bf16* Pp_, const bf16* LO, const float* mu, const float* w0, const float* a0, const float* k_k, const float* k_a, const float* r_k, ...
;     ...
;         for (int t = 0; t < 16; ++t) {
;             const float r0 = bf2f(sr_[t + 1]), k0 = bf2f(sk_[t + 1]), v0 = bf2f(sv_[t + 1]);
;             const float r = r0 + (r1 - r0) * mu_r, k = k0 + (k1 - k0) * mu_k, v = v0 + (v1 - v0) * mu_v; r1 = r0; k1 = k0; v1 = v0;
;             const float z = -(w0c + bf2f(slw[t])); const float sp = fmaxf(z, 0.f) + flog(1.0f + fexp(-fabsf(z))); const float w = -sp - 0.5f;
;             const float dec = fexp(-fexp(w)); const float a = fsigmoid(a0c + bf2f(sla[t]));
;             float kk = k * kkc; const float n2 = wsum_dpp(kk * kk); kk = kk / fmaxf(sqrtf(n2), 1e-12f);
;             const float kp = bf2f(f2bf(k * (1.0f + (a - 1.0f) * kac))), bb = bf2f(f2bf(kk * a)), rr = bf2f(f2bf(r)); kk = bf2f(f2bf(kk));
;             const float coef = wsum_dpp(rr * kp * rkc);
;             SV[(ib + t) * 64 + lane] = f2bf(v);
;             if (lane == 0) COEF[(size_t)(m0 + t) * 16 + h] = coef;
;             const float Pp = P; P *= dec; const float inv = 1.0f / P;
;             XKK[t * 72 + lane] = f2bf(kk * Pp); XR[t * 72 + lane] = f2bf(rr * P); XK[t * 72 + lane] = f2bf(kp * inv); XB[t * 72 + lane] = f2bf(bb * inv); }
.LBB0_283:
	s_or_b64 exec, exec, s[4:5]
	v_lshlrev_b32_e32 v96, 16, v132
	v_add_f32_e32 v96, v8, v96
	v_mul_f32_e64 v132, |v96|, s19
	v_exp_f32_e32 v132, v132
	v_mov_b32_e32 v140, s8
	v_mov_b32_e32 v141, s9
	v_add_f32_e32 v140, s7, v140
	v_add_f32_e32 v132, 1.0, v132
	v_log_f32_e32 v132, v132
	v_add_f32_e32 v141, s6, v141
	v_max_f32_e64 v96, -v96, 0
	v_add_f32_e32 v140, v140, v141
	v_fmac_f32_e32 v96, 0x3f317218, v132
	v_mul_f32_e32 v132, 0x4f800000, v140
	v_cmp_gt_f32_e32 vcc, s33, v140
	v_sub_f32_e32 v96, -0.5, v96
	v_mul_f32_e32 v96, 0x3fb8aa3b, v96
	v_cndmask_b32_e32 v132, v140, v132, vcc
	v_sqrt_f32_e32 v140, v132
	v_exp_f32_e32 v96, v96
	v_lshlrev_b32_e32 v128, 16, v128
	v_add_f32_e32 v128, v15, v128
	v_add_u32_e32 v141, -1, v140
	v_fma_f32 v142, -v141, v140, v132
	v_cmp_ge_f32_e64 s[56:57], 0, v142
	v_add_u32_e32 v142, 1, v140
	v_mul_f32_e32 v96, 0xbfb8aa3b, v96
	v_cndmask_b32_e64 v141, v140, v141, s[56:57]
	v_fma_f32 v140, -v142, v140, v132
	v_cmp_lt_f32_e64 s[56:57], 0, v140
	v_exp_f32_e32 v96, v96
	v_mul_f32_e32 v128, 0xbfb8aa3b, v128
	v_cndmask_b32_e64 v140, v141, v142, s[56:57]
	v_mul_f32_e32 v141, 0x37800000, v140
	v_cndmask_b32_e32 v140, v140, v141, vcc
	v_cmp_class_f32_e32 vcc, v132, v219
	v_exp_f32_e32 v128, v128
	v_lshlrev_b32_e32 v130, 16, v130
	v_cndmask_b32_e32 v132, v140, v132, vcc
	v_max_f32_e32 v132, 0x2b8cbccc, v132
	v_div_scale_f32 v140, s[0:1], v132, v132, v139
	v_rcp_f32_e32 v141, v140
	v_add_f32_e32 v128, 1.0, v128
	v_fma_f32 v142, -v140, v141, 1.0
	v_fmac_f32_e32 v141, v142, v141
	v_div_scale_f32 v142, vcc, v139, v132, v139
	v_mul_f32_e32 v143, v142, v141
	v_fma_f32 v144, -v140, v143, v142
	v_fmac_f32_e32 v143, v144, v141
	v_fma_f32 v140, -v140, v143, v142
	v_div_fmas_f32 v140, v140, v141, v143
	v_div_fixup_f32 v132, v140, v132, v139
	v_mul_f32_e32 v138, v138, v132
	v_cvt_pk_bf16_f32 v138, v138, s0
	v_div_scale_f32 v139, s[0:1], v96, v96, 1.0
	v_rcp_f32_e32 v140, v139
	s_nop 0
	v_cvt_pk_bf16_f32 v132, v132, s0
	v_lshlrev_b32_e32 v132, 16, v132
	v_cvt_pk_bf16_f32 v132, v132, s0
	v_fma_f32 v141, -v139, v140, 1.0
	v_fmac_f32_e32 v140, v141, v140
	v_div_scale_f32 v141, vcc, 1.0, v96, 1.0
	v_mul_f32_e32 v142, v141, v140
	v_fma_f32 v143, -v139, v142, v141
	v_fmac_f32_e32 v142, v143, v140
	v_fma_f32 v139, -v139, v142, v141
	v_div_fmas_f32 v139, v139, v140, v142
	ds_write_b16 v27, v132
	v_mul_f32_e32 v132, v96, v137
	v_div_fixup_f32 v139, v139, v96, 1.0
	v_cvt_pk_bf16_f32 v132, v132, s0
	ds_write_b16 v27, v132 offset:2304
	v_mul_f32_e32 v132, v139, v133
	v_lshlrev_b32_e32 v138, 16, v138
	v_cvt_pk_bf16_f32 v132, v132, s0
	ds_write_b16 v27, v132 offset:4608
	v_mul_f32_e32 v132, v139, v138
	v_cvt_pk_bf16_f32 v132, v132, s0
	v_sub_f32_e32 v133, v135, v130
	ds_write_b16 v27, v132 offset:6912
	v_lshlrev_b32_e32 v132, 16, v129
	v_lshlrev_b32_e32 v129, 16, v131
	v_fma_f32 v135, v9, v133, v130
	v_sub_f32_e32 v133, v134, v129
	v_mul_f32_e32 v134, v14, v135
	v_sub_f32_e32 v131, v136, v132
	v_fma_f32 v136, v12, v133, v129
	v_rcp_f32_e32 v133, v128
	v_mul_f32_e32 v128, v134, v134
	v_fma_f32 v131, v10, v131, v132
	v_cvt_pk_bf16_f32 v131, v131, s0
	v_mov_b32_dpp v128, v128 quad_perm:[1,0,3,2] row_mask:0xf bank_mask:0xf bound_ctrl:1
	v_fmac_f32_e32 v128, v134, v134
	v_lshlrev_b32_e32 v131, 16, v131
	s_nop 0
	v_add_f32_dpp v128, v128, v128 quad_perm:[2,3,0,1] row_mask:0xf bank_mask:0xf bound_ctrl:1
	s_nop 1
	v_add_f32_dpp v128, v128, v128 row_ror:4 row_mask:0xf bank_mask:0xf bound_ctrl:1
	s_nop 1
	v_add_f32_dpp v128, v128, v128 row_ror:8 row_mask:0xf bank_mask:0xf bound_ctrl:1
	s_nop 0
	v_readlane_b32 s7, v128, 0
	v_readlane_b32 s8, v128, 16
	v_readlane_b32 s6, v128, 32
	v_readlane_b32 s9, v128, 48
	v_add_f32_e32 v128, -1.0, v133
	v_fma_f32 v128, v13, v128, 1.0
	v_mul_f32_e32 v128, v135, v128
	v_cvt_pk_bf16_f32 v128, v128, s0
	v_lshlrev_b32_e32 v128, 16, v128
	v_mul_f32_e32 v135, v131, v128
	v_mul_f32_e32 v137, v11, v135
	s_nop 1
	v_mov_b32_dpp v137, v137 quad_perm:[1,0,3,2] row_mask:0xf bank_mask:0xf bound_ctrl:1
	v_fmac_f32_e32 v137, v11, v135
	s_nop 1
	v_add_f32_dpp v135, v137, v137 quad_perm:[2,3,0,1] row_mask:0xf bank_mask:0xf bound_ctrl:1
	s_nop 1
	v_add_f32_dpp v135, v135, v135 row_ror:4 row_mask:0xf bank_mask:0xf bound_ctrl:1
	s_nop 1
	v_add_f32_dpp v135, v135, v135 row_ror:8 row_mask:0xf bank_mask:0xf bound_ctrl:1
	s_nop 0
	v_readlane_b32 s0, v135, 0
	v_readlane_b32 s15, v135, 16
	v_readlane_b32 s1, v135, 32
	v_readlane_b32 s17, v135, 48
	v_cvt_pk_bf16_f32 v135, v136, s0
	global_store_short v[156:157], v135, off offset:128
	s_and_saveexec_b64 s[4:5], s[38:39]
	s_cbranch_execz .LBB0_285
	s_ashr_i32 s87, s86, 31
	s_lshl_b64 s[30:31], s[86:87], 6
	s_add_u32 s30, s2, s30
	v_mov_b32_e32 v136, s15
	v_mov_b32_e32 v137, s17
	s_addc_u32 s31, s14, s31
	v_pk_add_f32 v[136:137], s[0:1], v[136:137]
	s_nop 0
	v_add_f32_e32 v135, v136, v137
	v_mov_b64_e32 v[136:137], s[30:31]
	global_store_dword v[136:137], v135, off
; __device__ __forceinline__ float bf2f(bf16 b) { return __uint_as_float((unsigned)b << 16); }
; __device__ __forceinline__ bf16 f2bf(float f) { return (bf16)(pk_bf16(f, 0.f) & 0xffffu); }
; __device__ __forceinline__ float fexp(float x) { return __builtin_amdgcn_exp2f(x * 1.4426950408889634f); }
; __device__ __forceinline__ float flog(float x) { return __builtin_amdgcn_logf(x) * 0.6931471805599453f; }
; __device__ __forceinline__ float fsigmoid(float x) { return __builtin_amdgcn_rcpf(1.0f + fexp(-x)); }
; __device__ __forceinline__ void pc_phase(LAS unsigned char* lds, const bf16* Pp_, const bf16* LO, const float* mu, const float* w0, const float* a0, const float* k_k, const float* k_a, const float* r_k, ...
;     ...
;         for (int t = 0; t < 16; ++t) {
;             const float r0 = bf2f(sr_[t + 1]), k0 = bf2f(sk_[t + 1]), v0 = bf2f(sv_[t + 1]);
;             const float r = r0 + (r1 - r0) * mu_r, k = k0 + (k1 - k0) * mu_k, v = v0 + (v1 - v0) * mu_v; r1 = r0; k1 = k0; v1 = v0;
;             const float z = -(w0c + bf2f(slw[t])); const float sp = fmaxf(z, 0.f) + flog(1.0f + fexp(-fabsf(z))); const float w = -sp - 0.5f;
;             const float dec = fexp(-fexp(w)); const float a = fsigmoid(a0c + bf2f(sla[t]));
;             float kk = k * kkc; const float n2 = wsum_dpp(kk * kk); kk = kk / fmaxf(sqrtf(n2), 1e-12f);
;             const float kp = bf2f(f2bf(k * (1.0f + (a - 1.0f) * kac))), bb = bf2f(f2bf(kk * a)), rr = bf2f(f2bf(r)); kk = bf2f(f2bf(kk));
;             const float coef = wsum_dpp(rr * kp * rkc);
;             SV[(ib + t) * 64 + lane] = f2bf(v);
;             if (lane == 0) COEF[(size_t)(m0 + t) * 16 + h] = coef;
;             const float Pp = P; P *= dec; const float inv = 1.0f / P;
;             XKK[t * 72 + lane] = f2bf(kk * Pp); XR[t * 72 + lane] = f2bf(rr * P); XK[t * 72 + lane] = f2bf(kp * inv); XB[t * 72 + lane] = f2bf(bb * inv); }
.LBB0_285:
	s_or_b64 exec, exec, s[4:5]
	v_lshlrev_b32_e32 v127, 16, v127
	v_add_f32_e32 v127, v8, v127
	v_mul_f32_e64 v135, |v127|, s19
	v_exp_f32_e32 v135, v135
	v_mov_b32_e32 v136, s8
	v_mov_b32_e32 v137, s9
	v_add_f32_e32 v136, s7, v136
	v_add_f32_e32 v135, 1.0, v135
	v_log_f32_e32 v135, v135
	v_add_f32_e32 v137, s6, v137
	v_max_f32_e64 v127, -v127, 0
	v_add_f32_e32 v136, v136, v137
	v_fmac_f32_e32 v127, 0x3f317218, v135
	v_mul_f32_e32 v135, 0x4f800000, v136
	v_cmp_gt_f32_e32 vcc, s33, v136
	v_sub_f32_e32 v127, -0.5, v127
	v_mul_f32_e32 v127, 0x3fb8aa3b, v127
	v_cndmask_b32_e32 v135, v136, v135, vcc
	v_sqrt_f32_e32 v136, v135
	v_exp_f32_e32 v127, v127
	v_lshlrev_b32_e32 v123, 16, v123
	v_add_f32_e32 v123, v15, v123
	v_add_u32_e32 v137, -1, v136
	v_fma_f32 v138, -v137, v136, v135
	v_cmp_ge_f32_e64 s[56:57], 0, v138
	v_add_u32_e32 v138, 1, v136
	v_mul_f32_e32 v127, 0xbfb8aa3b, v127
	v_cndmask_b32_e64 v137, v136, v137, s[56:57]
	v_fma_f32 v136, -v138, v136, v135
	v_cmp_lt_f32_e64 s[56:57], 0, v136
	v_exp_f32_e32 v127, v127
	v_mul_f32_e32 v123, 0xbfb8aa3b, v123
	v_cndmask_b32_e64 v136, v137, v138, s[56:57]
	v_mul_f32_e32 v137, 0x37800000, v136
	v_cndmask_b32_e32 v136, v136, v137, vcc
	v_cmp_class_f32_e32 vcc, v135, v219
	v_mul_f32_e32 v127, v96, v127
	v_lshlrev_b32_e32 v125, 16, v125
	v_cndmask_b32_e32 v135, v136, v135, vcc
	v_max_f32_e32 v135, 0x2b8cbccc, v135
	v_div_scale_f32 v136, s[0:1], v135, v135, v134
	v_rcp_f32_e32 v137, v136
	v_exp_f32_e32 v123, v123
	v_fma_f32 v138, -v136, v137, 1.0
	v_fmac_f32_e32 v137, v138, v137
	v_div_scale_f32 v138, vcc, v134, v135, v134
	v_mul_f32_e32 v139, v138, v137
	v_fma_f32 v140, -v136, v139, v138
	v_fmac_f32_e32 v139, v140, v137
	v_fma_f32 v136, -v136, v139, v138
	v_div_fmas_f32 v136, v136, v137, v139
	v_div_fixup_f32 v134, v136, v135, v134
	v_mul_f32_e32 v133, v133, v134
	v_cvt_pk_bf16_f32 v133, v133, s0
	v_div_scale_f32 v135, s[0:1], v127, v127, 1.0
	v_rcp_f32_e32 v136, v135
	s_nop 0
	v_cvt_pk_bf16_f32 v134, v134, s0
	v_lshlrev_b32_e32 v134, 16, v134
	v_mul_f32_e32 v96, v96, v134
	v_fma_f32 v137, -v135, v136, 1.0
	v_fmac_f32_e32 v136, v137, v136
	v_div_scale_f32 v137, vcc, 1.0, v127, 1.0
	v_mul_f32_e32 v138, v137, v136
	v_fma_f32 v139, -v135, v138, v137
	v_fmac_f32_e32 v138, v139, v136
	v_fma_f32 v135, -v135, v138, v137
	v_cvt_pk_bf16_f32 v96, v96, s0
	v_div_fmas_f32 v135, v135, v136, v138
	ds_write_b16 v27, v96 offset:144
	v_mul_f32_e32 v96, v127, v131
	v_div_fixup_f32 v135, v135, v127, 1.0
	v_cvt_pk_bf16_f32 v96, v96, s0
	ds_write_b16 v27, v96 offset:2448
	v_mul_f32_e32 v96, v135, v128
	v_lshlrev_b32_e32 v133, 16, v133
	v_cvt_pk_bf16_f32 v96, v96, s0
	ds_write_b16 v27, v96 offset:4752
	v_mul_f32_e32 v96, v135, v133
	v_cvt_pk_bf16_f32 v96, v96, s0
	v_lshlrev_b32_e32 v128, 16, v124
	ds_write_b16 v27, v96 offset:7056
	v_sub_f32_e32 v96, v132, v128
	v_lshlrev_b32_e32 v124, 16, v126
	v_fma_f32 v126, v10, v96, v128
	v_sub_f32_e32 v96, v130, v125
	v_fma_f32 v130, v9, v96, v125
	v_sub_f32_e32 v96, v129, v124
	v_mul_f32_e32 v129, v14, v130
	v_fma_f32 v131, v12, v96, v124
	v_add_f32_e32 v96, 1.0, v123
	v_mul_f32_e32 v123, v129, v129
	v_rcp_f32_e32 v96, v96
	v_cvt_pk_bf16_f32 v126, v126, s0
	v_mov_b32_dpp v123, v123 quad_perm:[1,0,3,2] row_mask:0xf bank_mask:0xf bound_ctrl:1
	v_fmac_f32_e32 v123, v129, v129
	v_lshlrev_b32_e32 v126, 16, v126
	s_nop 0
	v_add_f32_dpp v123, v123, v123 quad_perm:[2,3,0,1] row_mask:0xf bank_mask:0xf bound_ctrl:1
	s_nop 1
	v_add_f32_dpp v123, v123, v123 row_ror:4 row_mask:0xf bank_mask:0xf bound_ctrl:1
	s_nop 1
	v_add_f32_dpp v123, v123, v123 row_ror:8 row_mask:0xf bank_mask:0xf bound_ctrl:1
	s_nop 0
	v_readlane_b32 s7, v123, 0
	v_readlane_b32 s8, v123, 16
	v_readlane_b32 s6, v123, 32
	v_readlane_b32 s9, v123, 48
	v_add_f32_e32 v123, -1.0, v96
	v_fma_f32 v123, v13, v123, 1.0
	v_mul_f32_e32 v123, v130, v123
	v_cvt_pk_bf16_f32 v123, v123, s0
	v_lshlrev_b32_e32 v123, 16, v123
	v_mul_f32_e32 v130, v126, v123
	v_mul_f32_e32 v132, v11, v130
	s_nop 1
	v_mov_b32_dpp v132, v132 quad_perm:[1,0,3,2] row_mask:0xf bank_mask:0xf bound_ctrl:1
	v_fmac_f32_e32 v132, v11, v130
	s_nop 1
	v_add_f32_dpp v130, v132, v132 quad_perm:[2,3,0,1] row_mask:0xf bank_mask:0xf bound_ctrl:1
	s_nop 1
	v_add_f32_dpp v130, v130, v130 row_ror:4 row_mask:0xf bank_mask:0xf bound_ctrl:1
	s_nop 1
	v_add_f32_dpp v130, v130, v130 row_ror:8 row_mask:0xf bank_mask:0xf bound_ctrl:1
	s_nop 0
	v_readlane_b32 s0, v130, 0
	v_readlane_b32 s15, v130, 16
	v_readlane_b32 s1, v130, 32
	v_readlane_b32 s17, v130, 48
	v_cvt_pk_bf16_f32 v132, v131, s0
	global_store_short v[156:157], v132, off offset:256
	s_and_saveexec_b64 s[4:5], s[38:39]
	s_cbranch_execz .LBB0_287
	s_mov_b32 s37, s35
	s_ashr_i32 s35, s34, 31
	s_lshl_b64 s[30:31], s[34:35], 6
	s_add_u32 s30, s2, s30
	v_mov_b32_e32 v130, s15
	v_mov_b32_e32 v131, s17
	s_addc_u32 s31, s14, s31
	v_pk_add_f32 v[130:131], s[0:1], v[130:131]
	s_mov_b32 s35, s37
	v_add_f32_e32 v132, v130, v131
	v_mov_b64_e32 v[130:131], s[30:31]
	global_store_dword v[130:131], v132, off
; __device__ __forceinline__ float bf2f(bf16 b) { return __uint_as_float((unsigned)b << 16); }
; __device__ __forceinline__ bf16 f2bf(float f) { return (bf16)(pk_bf16(f, 0.f) & 0xffffu); }
; __device__ __forceinline__ float fexp(float x) { return __builtin_amdgcn_exp2f(x * 1.4426950408889634f); }
; __device__ __forceinline__ float flog(float x) { return __builtin_amdgcn_logf(x) * 0.6931471805599453f; }
; __device__ __forceinline__ float fsigmoid(float x) { return __builtin_amdgcn_rcpf(1.0f + fexp(-x)); }
; __device__ __forceinline__ void pc_phase(LAS unsigned char* lds, const bf16* Pp_, const bf16* LO, const float* mu, const float* w0, const float* a0, const float* k_k, const float* k_a, const float* r_k, ...
;     ...
;         for (int t = 0; t < 16; ++t) {
;             const float r0 = bf2f(sr_[t + 1]), k0 = bf2f(sk_[t + 1]), v0 = bf2f(sv_[t + 1]);
;             const float r = r0 + (r1 - r0) * mu_r, k = k0 + (k1 - k0) * mu_k, v = v0 + (v1 - v0) * mu_v; r1 = r0; k1 = k0; v1 = v0;
;             const float z = -(w0c + bf2f(slw[t])); const float sp = fmaxf(z, 0.f) + flog(1.0f + fexp(-fabsf(z))); const float w = -sp - 0.5f;
;             const float dec = fexp(-fexp(w)); const float a = fsigmoid(a0c + bf2f(sla[t]));
;             float kk = k * kkc; const float n2 = wsum_dpp(kk * kk); kk = kk / fmaxf(sqrtf(n2), 1e-12f);
;             const float kp = bf2f(f2bf(k * (1.0f + (a - 1.0f) * kac))), bb = bf2f(f2bf(kk * a)), rr = bf2f(f2bf(r)); kk = bf2f(f2bf(kk));
;             const float coef = wsum_dpp(rr * kp * rkc);
;             SV[(ib + t) * 64 + lane] = f2bf(v);
;             if (lane == 0) COEF[(size_t)(m0 + t) * 16 + h] = coef;
;             const float Pp = P; P *= dec; const float inv = 1.0f / P;
;             XKK[t * 72 + lane] = f2bf(kk * Pp); XR[t * 72 + lane] = f2bf(rr * P); XK[t * 72 + lane] = f2bf(kp * inv); XB[t * 72 + lane] = f2bf(bb * inv); }
.LBB0_287:
	s_or_b64 exec, exec, s[4:5]
	v_lshlrev_b32_e32 v122, 16, v122
	v_add_f32_e32 v122, v8, v122
	v_mul_f32_e64 v130, |v122|, s19
	v_exp_f32_e32 v130, v130
	v_mov_b32_e32 v131, s8
	v_mov_b32_e32 v132, s9
	v_add_f32_e32 v131, s7, v131
	v_add_f32_e32 v130, 1.0, v130
	v_log_f32_e32 v130, v130
	v_add_f32_e32 v132, s6, v132
	v_max_f32_e64 v122, -v122, 0
	v_add_f32_e32 v131, v131, v132
	v_fmac_f32_e32 v122, 0x3f317218, v130
	v_mul_f32_e32 v130, 0x4f800000, v131
	v_cmp_gt_f32_e32 vcc, s33, v131
	v_sub_f32_e32 v122, -0.5, v122
	v_mul_f32_e32 v122, 0x3fb8aa3b, v122
	v_cndmask_b32_e32 v130, v131, v130, vcc
	v_sqrt_f32_e32 v131, v130
	v_exp_f32_e32 v122, v122
	v_lshlrev_b32_e32 v118, 16, v118
	v_add_f32_e32 v118, v15, v118
	v_add_u32_e32 v132, -1, v131
	v_fma_f32 v133, -v132, v131, v130
	v_cmp_ge_f32_e64 s[56:57], 0, v133
	v_add_u32_e32 v133, 1, v131
	v_mul_f32_e32 v122, 0xbfb8aa3b, v122
	v_cndmask_b32_e64 v132, v131, v132, s[56:57]
	v_fma_f32 v131, -v133, v131, v130
	v_cmp_lt_f32_e64 s[56:57], 0, v131
	v_exp_f32_e32 v122, v122
	v_mul_f32_e32 v118, 0xbfb8aa3b, v118
	v_cndmask_b32_e64 v131, v132, v133, s[56:57]
	v_mul_f32_e32 v132, 0x37800000, v131
	v_cndmask_b32_e32 v131, v131, v132, vcc
	v_cmp_class_f32_e32 vcc, v130, v219
	v_exp_f32_e32 v118, v118
	v_lshlrev_b32_e32 v120, 16, v120
	v_cndmask_b32_e32 v130, v131, v130, vcc
	v_max_f32_e32 v130, 0x2b8cbccc, v130
	v_div_scale_f32 v131, s[0:1], v130, v130, v129
	v_rcp_f32_e32 v132, v131
	v_add_f32_e32 v118, 1.0, v118
	v_fma_f32 v133, -v131, v132, 1.0
	v_fmac_f32_e32 v132, v133, v132
	v_div_scale_f32 v133, vcc, v129, v130, v129
	v_mul_f32_e32 v134, v133, v132
	v_fma_f32 v135, -v131, v134, v133
	v_fmac_f32_e32 v134, v135, v132
	v_fma_f32 v131, -v131, v134, v133
	v_div_fmas_f32 v131, v131, v132, v134
	v_div_fixup_f32 v129, v131, v130, v129
	v_mul_f32_e32 v96, v96, v129
	v_cvt_pk_bf16_f32 v130, v96, s0
	v_mul_f32_e32 v96, v127, v122
	v_div_scale_f32 v122, s[0:1], v96, v96, 1.0
	v_rcp_f32_e32 v131, v122
	v_lshlrev_b32_e32 v130, 16, v130
	v_mul_f32_e32 v126, v96, v126
	v_cvt_pk_bf16_f32 v126, v126, s0
	v_fma_f32 v132, -v122, v131, 1.0
	v_fmac_f32_e32 v131, v132, v131
	v_div_scale_f32 v132, vcc, 1.0, v96, 1.0
	v_mul_f32_e32 v133, v132, v131
	v_fma_f32 v134, -v122, v133, v132
	v_fmac_f32_e32 v133, v134, v131
	v_fma_f32 v122, -v122, v133, v132
	v_div_fmas_f32 v122, v122, v131, v133
	v_div_fixup_f32 v122, v122, v96, 1.0
	v_mul_f32_e32 v123, v122, v123
	v_cvt_pk_bf16_f32 v123, v123, s0
	v_mul_f32_e32 v122, v122, v130
	ds_write_b16 v27, v123 offset:4896
	v_cvt_pk_bf16_f32 v122, v122, s0
	v_sub_f32_e32 v123, v125, v120
	ds_write_b16 v27, v122 offset:7200
	v_lshlrev_b32_e32 v122, 16, v119
	v_lshlrev_b32_e32 v119, 16, v121
	v_fma_f32 v125, v9, v123, v120
	v_sub_f32_e32 v123, v124, v119
	v_mul_f32_e32 v124, v14, v125
	ds_write_b16 v27, v126 offset:2592
	v_fma_f32 v126, v12, v123, v119
	v_rcp_f32_e32 v123, v118
	v_mul_f32_e32 v118, v124, v124
	v_sub_f32_e32 v121, v128, v122
	v_cvt_pk_bf16_f32 v129, v129, s0
	v_mov_b32_dpp v118, v118 quad_perm:[1,0,3,2] row_mask:0xf bank_mask:0xf bound_ctrl:1
	v_fmac_f32_e32 v118, v124, v124
	v_fma_f32 v121, v10, v121, v122
	v_lshlrev_b32_e32 v129, 16, v129
	v_add_f32_dpp v118, v118, v118 quad_perm:[2,3,0,1] row_mask:0xf bank_mask:0xf bound_ctrl:1
	v_cvt_pk_bf16_f32 v121, v121, s0
	v_mul_f32_e32 v127, v127, v129
	v_add_f32_dpp v118, v118, v118 row_ror:4 row_mask:0xf bank_mask:0xf bound_ctrl:1
	v_lshlrev_b32_e32 v121, 16, v121
	v_cvt_pk_bf16_f32 v127, v127, s0
	v_add_f32_dpp v118, v118, v118 row_ror:8 row_mask:0xf bank_mask:0xf bound_ctrl:1
	ds_write_b16 v27, v127 offset:288
	v_readlane_b32 s7, v118, 0
	v_readlane_b32 s8, v118, 16
	v_readlane_b32 s6, v118, 32
	v_readlane_b32 s9, v118, 48
	v_add_f32_e32 v118, -1.0, v123
	v_fma_f32 v118, v13, v118, 1.0
	v_mul_f32_e32 v118, v125, v118
	v_cvt_pk_bf16_f32 v118, v118, s0
	v_lshlrev_b32_e32 v118, 16, v118
	v_mul_f32_e32 v125, v121, v118
	v_mul_f32_e32 v127, v11, v125
	s_nop 1
	v_mov_b32_dpp v127, v127 quad_perm:[1,0,3,2] row_mask:0xf bank_mask:0xf bound_ctrl:1
	v_fmac_f32_e32 v127, v11, v125
	s_nop 1
	v_add_f32_dpp v125, v127, v127 quad_perm:[2,3,0,1] row_mask:0xf bank_mask:0xf bound_ctrl:1
	s_nop 1
	v_add_f32_dpp v125, v125, v125 row_ror:4 row_mask:0xf bank_mask:0xf bound_ctrl:1
	s_nop 1
	v_add_f32_dpp v125, v125, v125 row_ror:8 row_mask:0xf bank_mask:0xf bound_ctrl:1
	s_nop 0
	v_readlane_b32 s0, v125, 0
	v_readlane_b32 s15, v125, 16
	v_readlane_b32 s1, v125, 32
	v_readlane_b32 s17, v125, 48
	v_cvt_pk_bf16_f32 v125, v126, s0
	global_store_short v[156:157], v125, off offset:384
	s_and_saveexec_b64 s[4:5], s[38:39]
	s_cbranch_execz .LBB0_289
	s_ashr_i32 s41, s40, 31
	s_lshl_b64 s[30:31], s[40:41], 6
	s_add_u32 s30, s2, s30
	v_mov_b32_e32 v126, s15
	v_mov_b32_e32 v127, s17
	s_addc_u32 s31, s14, s31
	v_pk_add_f32 v[126:127], s[0:1], v[126:127]
	s_nop 0
	v_add_f32_e32 v125, v126, v127
	v_mov_b64_e32 v[126:127], s[30:31]
	global_store_dword v[126:127], v125, off
; __device__ __forceinline__ float bf2f(bf16 b) { return __uint_as_float((unsigned)b << 16); }
; __device__ __forceinline__ bf16 f2bf(float f) { return (bf16)(pk_bf16(f, 0.f) & 0xffffu); }
; __device__ __forceinline__ float fexp(float x) { return __builtin_amdgcn_exp2f(x * 1.4426950408889634f); }
; __device__ __forceinline__ float flog(float x) { return __builtin_amdgcn_logf(x) * 0.6931471805599453f; }
; __device__ __forceinline__ float fsigmoid(float x) { return __builtin_amdgcn_rcpf(1.0f + fexp(-x)); }
; __device__ __forceinline__ void pc_phase(LAS unsigned char* lds, const bf16* Pp_, const bf16* LO, const float* mu, const float* w0, const float* a0, const float* k_k, const float* k_a, const float* r_k, ...
;     ...
;         for (int t = 0; t < 16; ++t) {
;             const float r0 = bf2f(sr_[t + 1]), k0 = bf2f(sk_[t + 1]), v0 = bf2f(sv_[t + 1]);
;             const float r = r0 + (r1 - r0) * mu_r, k = k0 + (k1 - k0) * mu_k, v = v0 + (v1 - v0) * mu_v; r1 = r0; k1 = k0; v1 = v0;
;             const float z = -(w0c + bf2f(slw[t])); const float sp = fmaxf(z, 0.f) + flog(1.0f + fexp(-fabsf(z))); const float w = -sp - 0.5f;
;             const float dec = fexp(-fexp(w)); const float a = fsigmoid(a0c + bf2f(sla[t]));
;             float kk = k * kkc; const float n2 = wsum_dpp(kk * kk); kk = kk / fmaxf(sqrtf(n2), 1e-12f);
;             const float kp = bf2f(f2bf(k * (1.0f + (a - 1.0f) * kac))), bb = bf2f(f2bf(kk * a)), rr = bf2f(f2bf(r)); kk = bf2f(f2bf(kk));
;             const float coef = wsum_dpp(rr * kp * rkc);
;             SV[(ib + t) * 64 + lane] = f2bf(v);
;             if (lane == 0) COEF[(size_t)(m0 + t) * 16 + h] = coef;
;             const float Pp = P; P *= dec; const float inv = 1.0f / P;
;             XKK[t * 72 + lane] = f2bf(kk * Pp); XR[t * 72 + lane] = f2bf(rr * P); XK[t * 72 + lane] = f2bf(kp * inv); XB[t * 72 + lane] = f2bf(bb * inv); }
.LBB0_289:
	s_or_b64 exec, exec, s[4:5]
	v_lshlrev_b32_e32 v117, 16, v117
	v_add_f32_e32 v117, v8, v117
	v_mul_f32_e64 v125, |v117|, s19
	v_exp_f32_e32 v125, v125
	v_mov_b32_e32 v126, s8
	v_mov_b32_e32 v127, s9
	v_add_f32_e32 v126, s7, v126
	v_add_f32_e32 v125, 1.0, v125
	v_log_f32_e32 v125, v125
	v_add_f32_e32 v127, s6, v127
	v_max_f32_e64 v117, -v117, 0
	v_add_f32_e32 v126, v126, v127
	v_fmac_f32_e32 v117, 0x3f317218, v125
	v_mul_f32_e32 v125, 0x4f800000, v126
	v_cmp_gt_f32_e32 vcc, s33, v126
	v_sub_f32_e32 v117, -0.5, v117
	v_mul_f32_e32 v117, 0x3fb8aa3b, v117
	v_cndmask_b32_e32 v125, v126, v125, vcc
	v_sqrt_f32_e32 v126, v125
	v_exp_f32_e32 v117, v117
	v_lshlrev_b32_e32 v113, 16, v113
	v_add_f32_e32 v113, v15, v113
	v_add_u32_e32 v127, -1, v126
	v_fma_f32 v128, -v127, v126, v125
	v_cmp_ge_f32_e64 s[56:57], 0, v128
	v_add_u32_e32 v128, 1, v126
	v_mul_f32_e32 v117, 0xbfb8aa3b, v117
	v_cndmask_b32_e64 v127, v126, v127, s[56:57]
	v_fma_f32 v126, -v128, v126, v125
	v_cmp_lt_f32_e64 s[56:57], 0, v126
	v_exp_f32_e32 v117, v117
	v_mul_f32_e32 v113, 0xbfb8aa3b, v113
	v_cndmask_b32_e64 v126, v127, v128, s[56:57]
	v_mul_f32_e32 v127, 0x37800000, v126
	v_cndmask_b32_e32 v126, v126, v127, vcc
	v_cmp_class_f32_e32 vcc, v125, v219
	v_mul_f32_e32 v117, v96, v117
	v_lshlrev_b32_e32 v115, 16, v115
	v_cndmask_b32_e32 v125, v126, v125, vcc
	v_max_f32_e32 v125, 0x2b8cbccc, v125
	v_div_scale_f32 v126, s[0:1], v125, v125, v124
	v_rcp_f32_e32 v127, v126
	v_exp_f32_e32 v113, v113
	v_fma_f32 v128, -v126, v127, 1.0
	v_fmac_f32_e32 v127, v128, v127
	v_div_scale_f32 v128, vcc, v124, v125, v124
	v_mul_f32_e32 v129, v128, v127
	v_fma_f32 v130, -v126, v129, v128
	v_fmac_f32_e32 v129, v130, v127
	v_fma_f32 v126, -v126, v129, v128
	v_div_fmas_f32 v126, v126, v127, v129
	v_div_fixup_f32 v124, v126, v125, v124
	v_mul_f32_e32 v123, v123, v124
	v_cvt_pk_bf16_f32 v123, v123, s0
	v_div_scale_f32 v125, s[0:1], v117, v117, 1.0
	v_rcp_f32_e32 v126, v125
	s_nop 0
	v_cvt_pk_bf16_f32 v124, v124, s0
	v_lshlrev_b32_e32 v124, 16, v124
	v_mul_f32_e32 v96, v96, v124
	v_fma_f32 v127, -v125, v126, 1.0
	v_fmac_f32_e32 v126, v127, v126
	v_div_scale_f32 v127, vcc, 1.0, v117, 1.0
	v_mul_f32_e32 v128, v127, v126
	v_fma_f32 v129, -v125, v128, v127
	v_fmac_f32_e32 v128, v129, v126
	v_fma_f32 v125, -v125, v128, v127
	v_cvt_pk_bf16_f32 v96, v96, s0
	v_div_fmas_f32 v125, v125, v126, v128
	ds_write_b16 v27, v96 offset:432
	v_mul_f32_e32 v96, v117, v121
	v_div_fixup_f32 v125, v125, v117, 1.0
	v_cvt_pk_bf16_f32 v96, v96, s0
	ds_write_b16 v27, v96 offset:2736
	v_mul_f32_e32 v96, v125, v118
	v_lshlrev_b32_e32 v123, 16, v123
	v_cvt_pk_bf16_f32 v96, v96, s0
	ds_write_b16 v27, v96 offset:5040
	v_mul_f32_e32 v96, v125, v123
	v_cvt_pk_bf16_f32 v96, v96, s0
	v_lshlrev_b32_e32 v118, 16, v114
	ds_write_b16 v27, v96 offset:7344
	v_sub_f32_e32 v96, v122, v118
	v_lshlrev_b32_e32 v114, 16, v116
	v_fma_f32 v116, v10, v96, v118
	v_sub_f32_e32 v96, v120, v115
	v_fma_f32 v120, v9, v96, v115
	v_sub_f32_e32 v96, v119, v114
	v_mul_f32_e32 v119, v14, v120
	v_fma_f32 v121, v12, v96, v114
	v_add_f32_e32 v96, 1.0, v113
	v_mul_f32_e32 v113, v119, v119
	v_rcp_f32_e32 v96, v96
	v_cvt_pk_bf16_f32 v116, v116, s0
	v_mov_b32_dpp v113, v113 quad_perm:[1,0,3,2] row_mask:0xf bank_mask:0xf bound_ctrl:1
	v_fmac_f32_e32 v113, v119, v119
	v_lshlrev_b32_e32 v116, 16, v116
	s_nop 0
	v_add_f32_dpp v113, v113, v113 quad_perm:[2,3,0,1] row_mask:0xf bank_mask:0xf bound_ctrl:1
	s_nop 1
	v_add_f32_dpp v113, v113, v113 row_ror:4 row_mask:0xf bank_mask:0xf bound_ctrl:1
	s_nop 1
	v_add_f32_dpp v113, v113, v113 row_ror:8 row_mask:0xf bank_mask:0xf bound_ctrl:1
	s_nop 0
	v_readlane_b32 s7, v113, 0
	v_readlane_b32 s8, v113, 16
	v_readlane_b32 s6, v113, 32
	v_readlane_b32 s9, v113, 48
	v_add_f32_e32 v113, -1.0, v96
	v_fma_f32 v113, v13, v113, 1.0
	v_mul_f32_e32 v113, v120, v113
	v_cvt_pk_bf16_f32 v113, v113, s0
	v_lshlrev_b32_e32 v113, 16, v113
	v_mul_f32_e32 v120, v116, v113
	v_mul_f32_e32 v122, v11, v120
	s_nop 1
	v_mov_b32_dpp v122, v122 quad_perm:[1,0,3,2] row_mask:0xf bank_mask:0xf bound_ctrl:1
	v_fmac_f32_e32 v122, v11, v120
	s_nop 1
	v_add_f32_dpp v120, v122, v122 quad_perm:[2,3,0,1] row_mask:0xf bank_mask:0xf bound_ctrl:1
	s_nop 1
	v_add_f32_dpp v120, v120, v120 row_ror:4 row_mask:0xf bank_mask:0xf bound_ctrl:1
	s_nop 1
	v_add_f32_dpp v120, v120, v120 row_ror:8 row_mask:0xf bank_mask:0xf bound_ctrl:1
	s_nop 0
	v_readlane_b32 s0, v120, 0
	v_readlane_b32 s15, v120, 16
	v_readlane_b32 s1, v120, 32
	v_readlane_b32 s17, v120, 48
	v_cvt_pk_bf16_f32 v122, v121, s0
	global_store_short v[156:157], v122, off offset:512
	s_and_saveexec_b64 s[4:5], s[38:39]
	s_cbranch_execz .LBB0_291
	s_ashr_i32 s73, s72, 31
	s_lshl_b64 s[30:31], s[72:73], 6
	s_add_u32 s30, s2, s30
	v_mov_b32_e32 v120, s15
	v_mov_b32_e32 v121, s17
	s_addc_u32 s31, s14, s31
	v_pk_add_f32 v[120:121], s[0:1], v[120:121]
	s_nop 0
	v_add_f32_e32 v122, v120, v121
	v_mov_b64_e32 v[120:121], s[30:31]
	global_store_dword v[120:121], v122, off
; __device__ __forceinline__ float bf2f(bf16 b) { return __uint_as_float((unsigned)b << 16); }
; __device__ __forceinline__ bf16 f2bf(float f) { return (bf16)(pk_bf16(f, 0.f) & 0xffffu); }
; __device__ __forceinline__ float fexp(float x) { return __builtin_amdgcn_exp2f(x * 1.4426950408889634f); }
; __device__ __forceinline__ float flog(float x) { return __builtin_amdgcn_logf(x) * 0.6931471805599453f; }
; __device__ __forceinline__ float fsigmoid(float x) { return __builtin_amdgcn_rcpf(1.0f + fexp(-x)); }
; __device__ __forceinline__ void pc_phase(LAS unsigned char* lds, const bf16* Pp_, const bf16* LO, const float* mu, const float* w0, const float* a0, const float* k_k, const float* k_a, const float* r_k, ...
;     ...
;         for (int t = 0; t < 16; ++t) {
;             const float r0 = bf2f(sr_[t + 1]), k0 = bf2f(sk_[t + 1]), v0 = bf2f(sv_[t + 1]);
;             const float r = r0 + (r1 - r0) * mu_r, k = k0 + (k1 - k0) * mu_k, v = v0 + (v1 - v0) * mu_v; r1 = r0; k1 = k0; v1 = v0;
;             const float z = -(w0c + bf2f(slw[t])); const float sp = fmaxf(z, 0.f) + flog(1.0f + fexp(-fabsf(z))); const float w = -sp - 0.5f;
;             const float dec = fexp(-fexp(w)); const float a = fsigmoid(a0c + bf2f(sla[t]));
;             float kk = k * kkc; const float n2 = wsum_dpp(kk * kk); kk = kk / fmaxf(sqrtf(n2), 1e-12f);
;             const float kp = bf2f(f2bf(k * (1.0f + (a - 1.0f) * kac))), bb = bf2f(f2bf(kk * a)), rr = bf2f(f2bf(r)); kk = bf2f(f2bf(kk));
;             const float coef = wsum_dpp(rr * kp * rkc);
;             SV[(ib + t) * 64 + lane] = f2bf(v);
;             if (lane == 0) COEF[(size_t)(m0 + t) * 16 + h] = coef;
;             const float Pp = P; P *= dec; const float inv = 1.0f / P;
;             XKK[t * 72 + lane] = f2bf(kk * Pp); XR[t * 72 + lane] = f2bf(rr * P); XK[t * 72 + lane] = f2bf(kp * inv); XB[t * 72 + lane] = f2bf(bb * inv); }
.LBB0_291:
	s_or_b64 exec, exec, s[4:5]
	v_lshlrev_b32_e32 v112, 16, v112
	v_add_f32_e32 v112, v8, v112
	v_mul_f32_e64 v120, |v112|, s19
	v_exp_f32_e32 v120, v120
	v_mov_b32_e32 v121, s8
	v_mov_b32_e32 v122, s9
	v_add_f32_e32 v121, s7, v121
	v_add_f32_e32 v120, 1.0, v120
	v_log_f32_e32 v120, v120
	v_add_f32_e32 v122, s6, v122
	v_max_f32_e64 v112, -v112, 0
	v_add_f32_e32 v121, v121, v122
	v_fmac_f32_e32 v112, 0x3f317218, v120
	v_mul_f32_e32 v120, 0x4f800000, v121
	v_cmp_gt_f32_e32 vcc, s33, v121
	v_sub_f32_e32 v112, -0.5, v112
	v_mul_f32_e32 v112, 0x3fb8aa3b, v112
	v_cndmask_b32_e32 v120, v121, v120, vcc
	v_sqrt_f32_e32 v121, v120
	v_exp_f32_e32 v112, v112
	v_lshlrev_b32_e32 v108, 16, v108
	v_add_f32_e32 v108, v15, v108
	v_add_u32_e32 v122, -1, v121
	v_fma_f32 v123, -v122, v121, v120
	v_cmp_ge_f32_e64 s[56:57], 0, v123
	v_add_u32_e32 v123, 1, v121
	v_mul_f32_e32 v112, 0xbfb8aa3b, v112
	v_cndmask_b32_e64 v122, v121, v122, s[56:57]
	v_fma_f32 v121, -v123, v121, v120
	v_cmp_lt_f32_e64 s[56:57], 0, v121
	v_exp_f32_e32 v112, v112
	v_mul_f32_e32 v108, 0xbfb8aa3b, v108
	v_cndmask_b32_e64 v121, v122, v123, s[56:57]
	v_mul_f32_e32 v122, 0x37800000, v121
	v_cndmask_b32_e32 v121, v121, v122, vcc
	v_cmp_class_f32_e32 vcc, v120, v219
	v_exp_f32_e32 v108, v108
	v_lshlrev_b32_e32 v110, 16, v110
	v_cndmask_b32_e32 v120, v121, v120, vcc
	v_max_f32_e32 v120, 0x2b8cbccc, v120
	v_div_scale_f32 v121, s[0:1], v120, v120, v119
	v_rcp_f32_e32 v122, v121
	v_add_f32_e32 v108, 1.0, v108
	v_fma_f32 v123, -v121, v122, 1.0
	v_fmac_f32_e32 v122, v123, v122
	v_div_scale_f32 v123, vcc, v119, v120, v119
	v_mul_f32_e32 v124, v123, v122
	v_fma_f32 v125, -v121, v124, v123
	v_fmac_f32_e32 v124, v125, v122
	v_fma_f32 v121, -v121, v124, v123
	v_div_fmas_f32 v121, v121, v122, v124
	v_div_fixup_f32 v119, v121, v120, v119
	v_mul_f32_e32 v96, v96, v119
	v_cvt_pk_bf16_f32 v120, v96, s0
	v_mul_f32_e32 v96, v117, v112
	v_div_scale_f32 v112, s[0:1], v96, v96, 1.0
	v_rcp_f32_e32 v121, v112
	v_lshlrev_b32_e32 v120, 16, v120
	v_mul_f32_e32 v116, v96, v116
	v_cvt_pk_bf16_f32 v116, v116, s0
	v_fma_f32 v122, -v112, v121, 1.0
	v_fmac_f32_e32 v121, v122, v121
	v_div_scale_f32 v122, vcc, 1.0, v96, 1.0
	v_mul_f32_e32 v123, v122, v121
	v_fma_f32 v124, -v112, v123, v122
	v_fmac_f32_e32 v123, v124, v121
	v_fma_f32 v112, -v112, v123, v122
	v_div_fmas_f32 v112, v112, v121, v123
	v_div_fixup_f32 v112, v112, v96, 1.0
	v_mul_f32_e32 v113, v112, v113
	v_cvt_pk_bf16_f32 v113, v113, s0
	v_mul_f32_e32 v112, v112, v120
	ds_write_b16 v27, v113 offset:5184
	v_cvt_pk_bf16_f32 v112, v112, s0
	v_sub_f32_e32 v113, v115, v110
	ds_write_b16 v27, v112 offset:7488
	v_lshlrev_b32_e32 v112, 16, v109
	v_lshlrev_b32_e32 v109, 16, v111
	v_fma_f32 v115, v9, v113, v110
	v_sub_f32_e32 v113, v114, v109
	v_mul_f32_e32 v114, v14, v115
	ds_write_b16 v27, v116 offset:2880
	v_fma_f32 v116, v12, v113, v109
	v_rcp_f32_e32 v113, v108
	v_mul_f32_e32 v108, v114, v114
	v_sub_f32_e32 v111, v118, v112
	v_cvt_pk_bf16_f32 v119, v119, s0
	v_mov_b32_dpp v108, v108 quad_perm:[1,0,3,2] row_mask:0xf bank_mask:0xf bound_ctrl:1
	v_fmac_f32_e32 v108, v114, v114
	v_fma_f32 v111, v10, v111, v112
	v_lshlrev_b32_e32 v119, 16, v119
	v_add_f32_dpp v108, v108, v108 quad_perm:[2,3,0,1] row_mask:0xf bank_mask:0xf bound_ctrl:1
	v_cvt_pk_bf16_f32 v111, v111, s0
	v_mul_f32_e32 v117, v117, v119
	v_add_f32_dpp v108, v108, v108 row_ror:4 row_mask:0xf bank_mask:0xf bound_ctrl:1
	v_lshlrev_b32_e32 v111, 16, v111
	v_cvt_pk_bf16_f32 v117, v117, s0
	v_add_f32_dpp v108, v108, v108 row_ror:8 row_mask:0xf bank_mask:0xf bound_ctrl:1
	ds_write_b16 v27, v117 offset:576
	v_readlane_b32 s7, v108, 0
	v_readlane_b32 s8, v108, 16
	v_readlane_b32 s6, v108, 32
	v_readlane_b32 s9, v108, 48
	v_add_f32_e32 v108, -1.0, v113
	v_fma_f32 v108, v13, v108, 1.0
	v_mul_f32_e32 v108, v115, v108
	v_cvt_pk_bf16_f32 v108, v108, s0
	v_lshlrev_b32_e32 v108, 16, v108
	v_mul_f32_e32 v115, v111, v108
	v_mul_f32_e32 v117, v11, v115
	s_nop 1
	v_mov_b32_dpp v117, v117 quad_perm:[1,0,3,2] row_mask:0xf bank_mask:0xf bound_ctrl:1
	v_fmac_f32_e32 v117, v11, v115
	s_nop 1
	v_add_f32_dpp v115, v117, v117 quad_perm:[2,3,0,1] row_mask:0xf bank_mask:0xf bound_ctrl:1
	s_nop 1
	v_add_f32_dpp v115, v115, v115 row_ror:4 row_mask:0xf bank_mask:0xf bound_ctrl:1
	s_nop 1
	v_add_f32_dpp v115, v115, v115 row_ror:8 row_mask:0xf bank_mask:0xf bound_ctrl:1
	s_nop 0
	v_readlane_b32 s0, v115, 0
	v_readlane_b32 s15, v115, 16
	v_readlane_b32 s1, v115, 32
	v_readlane_b32 s17, v115, 48
	v_cvt_pk_bf16_f32 v115, v116, s0
	global_store_short v[156:157], v115, off offset:640
	s_and_saveexec_b64 s[4:5], s[38:39]
	s_cbranch_execz .LBB0_293
	s_ashr_i32 s69, s68, 31
	s_lshl_b64 s[30:31], s[68:69], 6
	s_add_u32 s30, s2, s30
	v_mov_b32_e32 v116, s15
	v_mov_b32_e32 v117, s17
	s_addc_u32 s31, s14, s31
	v_pk_add_f32 v[116:117], s[0:1], v[116:117]
	s_nop 0
	v_add_f32_e32 v115, v116, v117
	v_mov_b64_e32 v[116:117], s[30:31]
	global_store_dword v[116:117], v115, off
; __device__ __forceinline__ float bf2f(bf16 b) { return __uint_as_float((unsigned)b << 16); }
; __device__ __forceinline__ bf16 f2bf(float f) { return (bf16)(pk_bf16(f, 0.f) & 0xffffu); }
; __device__ __forceinline__ float fexp(float x) { return __builtin_amdgcn_exp2f(x * 1.4426950408889634f); }
; __device__ __forceinline__ float flog(float x) { return __builtin_amdgcn_logf(x) * 0.6931471805599453f; }
; __device__ __forceinline__ float fsigmoid(float x) { return __builtin_amdgcn_rcpf(1.0f + fexp(-x)); }
; __device__ __forceinline__ void pc_phase(LAS unsigned char* lds, const bf16* Pp_, const bf16* LO, const float* mu, const float* w0, const float* a0, const float* k_k, const float* k_a, const float* r_k, ...
;     ...
;         for (int t = 0; t < 16; ++t) {
;             const float r0 = bf2f(sr_[t + 1]), k0 = bf2f(sk_[t + 1]), v0 = bf2f(sv_[t + 1]);
;             const float r = r0 + (r1 - r0) * mu_r, k = k0 + (k1 - k0) * mu_k, v = v0 + (v1 - v0) * mu_v; r1 = r0; k1 = k0; v1 = v0;
;             const float z = -(w0c + bf2f(slw[t])); const float sp = fmaxf(z, 0.f) + flog(1.0f + fexp(-fabsf(z))); const float w = -sp - 0.5f;
;             const float dec = fexp(-fexp(w)); const float a = fsigmoid(a0c + bf2f(sla[t]));
;             float kk = k * kkc; const float n2 = wsum_dpp(kk * kk); kk = kk / fmaxf(sqrtf(n2), 1e-12f);
;             const float kp = bf2f(f2bf(k * (1.0f + (a - 1.0f) * kac))), bb = bf2f(f2bf(kk * a)), rr = bf2f(f2bf(r)); kk = bf2f(f2bf(kk));
;             const float coef = wsum_dpp(rr * kp * rkc);
;             SV[(ib + t) * 64 + lane] = f2bf(v);
;             if (lane == 0) COEF[(size_t)(m0 + t) * 16 + h] = coef;
;             const float Pp = P; P *= dec; const float inv = 1.0f / P;
;             XKK[t * 72 + lane] = f2bf(kk * Pp); XR[t * 72 + lane] = f2bf(rr * P); XK[t * 72 + lane] = f2bf(kp * inv); XB[t * 72 + lane] = f2bf(bb * inv); }
.LBB0_293:
	s_or_b64 exec, exec, s[4:5]
	v_lshlrev_b32_e32 v107, 16, v107
	v_add_f32_e32 v107, v8, v107
	v_mul_f32_e64 v115, |v107|, s19
	v_exp_f32_e32 v115, v115
	v_mov_b32_e32 v116, s8
	v_mov_b32_e32 v117, s9
	v_add_f32_e32 v116, s7, v116
	v_add_f32_e32 v115, 1.0, v115
	v_log_f32_e32 v115, v115
	v_add_f32_e32 v117, s6, v117
	v_max_f32_e64 v107, -v107, 0
	v_add_f32_e32 v116, v116, v117
	v_fmac_f32_e32 v107, 0x3f317218, v115
	v_mul_f32_e32 v115, 0x4f800000, v116
	v_cmp_gt_f32_e32 vcc, s33, v116
	v_sub_f32_e32 v107, -0.5, v107
	v_mul_f32_e32 v107, 0x3fb8aa3b, v107
	v_cndmask_b32_e32 v115, v116, v115, vcc
	v_sqrt_f32_e32 v116, v115
	v_exp_f32_e32 v107, v107
	v_lshlrev_b32_e32 v103, 16, v103
	v_add_f32_e32 v103, v15, v103
	v_add_u32_e32 v117, -1, v116
	v_fma_f32 v118, -v117, v116, v115
	v_cmp_ge_f32_e64 s[56:57], 0, v118
	v_add_u32_e32 v118, 1, v116
	v_mul_f32_e32 v107, 0xbfb8aa3b, v107
	v_cndmask_b32_e64 v117, v116, v117, s[56:57]
	v_fma_f32 v116, -v118, v116, v115
	v_cmp_lt_f32_e64 s[56:57], 0, v116
	v_exp_f32_e32 v107, v107
	v_mul_f32_e32 v103, 0xbfb8aa3b, v103
	v_cndmask_b32_e64 v116, v117, v118, s[56:57]
	v_mul_f32_e32 v117, 0x37800000, v116
	v_cndmask_b32_e32 v116, v116, v117, vcc
	v_cmp_class_f32_e32 vcc, v115, v219
	v_mul_f32_e32 v107, v96, v107
	v_lshlrev_b32_e32 v105, 16, v105
	v_cndmask_b32_e32 v115, v116, v115, vcc
	v_max_f32_e32 v115, 0x2b8cbccc, v115
	v_div_scale_f32 v116, s[0:1], v115, v115, v114
	v_rcp_f32_e32 v117, v116
	v_exp_f32_e32 v103, v103
	v_fma_f32 v118, -v116, v117, 1.0
	v_fmac_f32_e32 v117, v118, v117
	v_div_scale_f32 v118, vcc, v114, v115, v114
	v_mul_f32_e32 v119, v118, v117
	v_fma_f32 v120, -v116, v119, v118
	v_fmac_f32_e32 v119, v120, v117
	v_fma_f32 v116, -v116, v119, v118
	v_div_fmas_f32 v116, v116, v117, v119
	v_div_fixup_f32 v114, v116, v115, v114
	v_mul_f32_e32 v113, v113, v114
	v_cvt_pk_bf16_f32 v113, v113, s0
	v_div_scale_f32 v115, s[0:1], v107, v107, 1.0
	v_rcp_f32_e32 v116, v115
	s_nop 0
	v_cvt_pk_bf16_f32 v114, v114, s0
	v_lshlrev_b32_e32 v114, 16, v114
	v_mul_f32_e32 v96, v96, v114
	v_fma_f32 v117, -v115, v116, 1.0
	v_fmac_f32_e32 v116, v117, v116
	v_div_scale_f32 v117, vcc, 1.0, v107, 1.0
	v_mul_f32_e32 v118, v117, v116
	v_fma_f32 v119, -v115, v118, v117
	v_fmac_f32_e32 v118, v119, v116
	v_fma_f32 v115, -v115, v118, v117
	v_cvt_pk_bf16_f32 v96, v96, s0
	v_div_fmas_f32 v115, v115, v116, v118
	ds_write_b16 v27, v96 offset:720
	v_mul_f32_e32 v96, v107, v111
	v_div_fixup_f32 v115, v115, v107, 1.0
	v_cvt_pk_bf16_f32 v96, v96, s0
	ds_write_b16 v27, v96 offset:3024
	v_mul_f32_e32 v96, v115, v108
	v_lshlrev_b32_e32 v113, 16, v113
	v_cvt_pk_bf16_f32 v96, v96, s0
	ds_write_b16 v27, v96 offset:5328
	v_mul_f32_e32 v96, v115, v113
	v_cvt_pk_bf16_f32 v96, v96, s0
	v_lshlrev_b32_e32 v108, 16, v104
	ds_write_b16 v27, v96 offset:7632
	v_sub_f32_e32 v96, v112, v108
	v_lshlrev_b32_e32 v104, 16, v106
	v_fma_f32 v106, v10, v96, v108
	v_sub_f32_e32 v96, v110, v105
	v_fma_f32 v110, v9, v96, v105
	v_sub_f32_e32 v96, v109, v104
	v_mul_f32_e32 v109, v14, v110
	v_fma_f32 v111, v12, v96, v104
	v_add_f32_e32 v96, 1.0, v103
	v_mul_f32_e32 v103, v109, v109
	v_rcp_f32_e32 v96, v96
	v_cvt_pk_bf16_f32 v106, v106, s0
	v_mov_b32_dpp v103, v103 quad_perm:[1,0,3,2] row_mask:0xf bank_mask:0xf bound_ctrl:1
	v_fmac_f32_e32 v103, v109, v109
	v_lshlrev_b32_e32 v106, 16, v106
	s_nop 0
	v_add_f32_dpp v103, v103, v103 quad_perm:[2,3,0,1] row_mask:0xf bank_mask:0xf bound_ctrl:1
	s_nop 1
	v_add_f32_dpp v103, v103, v103 row_ror:4 row_mask:0xf bank_mask:0xf bound_ctrl:1
	s_nop 1
	v_add_f32_dpp v103, v103, v103 row_ror:8 row_mask:0xf bank_mask:0xf bound_ctrl:1
	s_nop 0
	v_readlane_b32 s7, v103, 0
	v_readlane_b32 s8, v103, 16
	v_readlane_b32 s6, v103, 32
	v_readlane_b32 s9, v103, 48
	v_add_f32_e32 v103, -1.0, v96
	v_fma_f32 v103, v13, v103, 1.0
	v_mul_f32_e32 v103, v110, v103
	v_cvt_pk_bf16_f32 v103, v103, s0
	v_lshlrev_b32_e32 v103, 16, v103
	v_mul_f32_e32 v110, v106, v103
	v_mul_f32_e32 v112, v11, v110
	s_nop 1
	v_mov_b32_dpp v112, v112 quad_perm:[1,0,3,2] row_mask:0xf bank_mask:0xf bound_ctrl:1
	v_fmac_f32_e32 v112, v11, v110
	s_nop 1
	v_add_f32_dpp v110, v112, v112 quad_perm:[2,3,0,1] row_mask:0xf bank_mask:0xf bound_ctrl:1
	s_nop 1
	v_add_f32_dpp v110, v110, v110 row_ror:4 row_mask:0xf bank_mask:0xf bound_ctrl:1
	s_nop 1
	v_add_f32_dpp v110, v110, v110 row_ror:8 row_mask:0xf bank_mask:0xf bound_ctrl:1
	s_nop 0
	v_readlane_b32 s0, v110, 0
	v_readlane_b32 s15, v110, 16
	v_readlane_b32 s1, v110, 32
	v_readlane_b32 s17, v110, 48
	v_cvt_pk_bf16_f32 v112, v111, s0
	global_store_short v[156:157], v112, off offset:768
	s_and_saveexec_b64 s[4:5], s[38:39]
	s_cbranch_execz .LBB0_295
	s_ashr_i32 s67, s66, 31
	s_lshl_b64 s[30:31], s[66:67], 6
	s_add_u32 s30, s2, s30
	v_mov_b32_e32 v110, s15
	v_mov_b32_e32 v111, s17
	s_addc_u32 s31, s14, s31
	v_pk_add_f32 v[110:111], s[0:1], v[110:111]
	s_nop 0
	v_add_f32_e32 v112, v110, v111
	v_mov_b64_e32 v[110:111], s[30:31]
	global_store_dword v[110:111], v112, off
; __device__ __forceinline__ float bf2f(bf16 b) { return __uint_as_float((unsigned)b << 16); }
; __device__ __forceinline__ bf16 f2bf(float f) { return (bf16)(pk_bf16(f, 0.f) & 0xffffu); }
; __device__ __forceinline__ float fexp(float x) { return __builtin_amdgcn_exp2f(x * 1.4426950408889634f); }
; __device__ __forceinline__ float flog(float x) { return __builtin_amdgcn_logf(x) * 0.6931471805599453f; }
; __device__ __forceinline__ float fsigmoid(float x) { return __builtin_amdgcn_rcpf(1.0f + fexp(-x)); }
; __device__ __forceinline__ void pc_phase(LAS unsigned char* lds, const bf16* Pp_, const bf16* LO, const float* mu, const float* w0, const float* a0, const float* k_k, const float* k_a, const float* r_k, ...
;     ...
;         for (int t = 0; t < 16; ++t) {
;             const float r0 = bf2f(sr_[t + 1]), k0 = bf2f(sk_[t + 1]), v0 = bf2f(sv_[t + 1]);
;             const float r = r0 + (r1 - r0) * mu_r, k = k0 + (k1 - k0) * mu_k, v = v0 + (v1 - v0) * mu_v; r1 = r0; k1 = k0; v1 = v0;
;             const float z = -(w0c + bf2f(slw[t])); const float sp = fmaxf(z, 0.f) + flog(1.0f + fexp(-fabsf(z))); const float w = -sp - 0.5f;
;             const float dec = fexp(-fexp(w)); const float a = fsigmoid(a0c + bf2f(sla[t]));
;             float kk = k * kkc; const float n2 = wsum_dpp(kk * kk); kk = kk / fmaxf(sqrtf(n2), 1e-12f);
;             const float kp = bf2f(f2bf(k * (1.0f + (a - 1.0f) * kac))), bb = bf2f(f2bf(kk * a)), rr = bf2f(f2bf(r)); kk = bf2f(f2bf(kk));
;             const float coef = wsum_dpp(rr * kp * rkc);
;             SV[(ib + t) * 64 + lane] = f2bf(v);
;             if (lane == 0) COEF[(size_t)(m0 + t) * 16 + h] = coef;
;             const float Pp = P; P *= dec; const float inv = 1.0f / P;
;             XKK[t * 72 + lane] = f2bf(kk * Pp); XR[t * 72 + lane] = f2bf(rr * P); XK[t * 72 + lane] = f2bf(kp * inv); XB[t * 72 + lane] = f2bf(bb * inv); }
.LBB0_295:
	s_or_b64 exec, exec, s[4:5]
	v_lshlrev_b32_e32 v102, 16, v102
	v_add_f32_e32 v102, v8, v102
	v_mul_f32_e64 v110, |v102|, s19
	v_exp_f32_e32 v110, v110
	v_mov_b32_e32 v111, s8
	v_mov_b32_e32 v112, s9
	v_add_f32_e32 v111, s7, v111
	v_add_f32_e32 v110, 1.0, v110
	v_log_f32_e32 v110, v110
	v_add_f32_e32 v112, s6, v112
	v_max_f32_e64 v102, -v102, 0
	v_add_f32_e32 v111, v111, v112
	v_fmac_f32_e32 v102, 0x3f317218, v110
	v_mul_f32_e32 v110, 0x4f800000, v111
	v_cmp_gt_f32_e32 vcc, s33, v111
	v_sub_f32_e32 v102, -0.5, v102
	v_mul_f32_e32 v102, 0x3fb8aa3b, v102
	v_cndmask_b32_e32 v110, v111, v110, vcc
	v_sqrt_f32_e32 v111, v110
	v_exp_f32_e32 v102, v102
	v_lshlrev_b32_e32 v98, 16, v98
	v_add_f32_e32 v98, v15, v98
	v_add_u32_e32 v112, -1, v111
	v_fma_f32 v113, -v112, v111, v110
	v_cmp_ge_f32_e64 s[56:57], 0, v113
	v_add_u32_e32 v113, 1, v111
	v_mul_f32_e32 v102, 0xbfb8aa3b, v102
	v_cndmask_b32_e64 v112, v111, v112, s[56:57]
	v_fma_f32 v111, -v113, v111, v110
	v_cmp_lt_f32_e64 s[56:57], 0, v111
	v_exp_f32_e32 v102, v102
	v_mul_f32_e32 v98, 0xbfb8aa3b, v98
	v_cndmask_b32_e64 v111, v112, v113, s[56:57]
	v_mul_f32_e32 v112, 0x37800000, v111
	v_cndmask_b32_e32 v111, v111, v112, vcc
	v_cmp_class_f32_e32 vcc, v110, v219
	v_exp_f32_e32 v98, v98
	v_lshlrev_b32_e32 v100, 16, v100
	v_cndmask_b32_e32 v110, v111, v110, vcc
	v_max_f32_e32 v110, 0x2b8cbccc, v110
	v_div_scale_f32 v111, s[0:1], v110, v110, v109
	v_rcp_f32_e32 v112, v111
	v_add_f32_e32 v98, 1.0, v98
	v_fma_f32 v113, -v111, v112, 1.0
	v_fmac_f32_e32 v112, v113, v112
	v_div_scale_f32 v113, vcc, v109, v110, v109
	v_mul_f32_e32 v114, v113, v112
	v_fma_f32 v115, -v111, v114, v113
	v_fmac_f32_e32 v114, v115, v112
	v_fma_f32 v111, -v111, v114, v113
	v_div_fmas_f32 v111, v111, v112, v114
	v_div_fixup_f32 v109, v111, v110, v109
	v_mul_f32_e32 v96, v96, v109
	v_cvt_pk_bf16_f32 v110, v96, s0
	v_mul_f32_e32 v96, v107, v102
	v_div_scale_f32 v102, s[0:1], v96, v96, 1.0
	v_rcp_f32_e32 v111, v102
	v_lshlrev_b32_e32 v110, 16, v110
	v_mul_f32_e32 v106, v96, v106
	v_cvt_pk_bf16_f32 v106, v106, s0
	v_fma_f32 v112, -v102, v111, 1.0
	v_fmac_f32_e32 v111, v112, v111
	v_div_scale_f32 v112, vcc, 1.0, v96, 1.0
	v_mul_f32_e32 v113, v112, v111
	v_fma_f32 v114, -v102, v113, v112
	v_fmac_f32_e32 v113, v114, v111
	v_fma_f32 v102, -v102, v113, v112
	v_div_fmas_f32 v102, v102, v111, v113
	v_div_fixup_f32 v102, v102, v96, 1.0
	v_mul_f32_e32 v103, v102, v103
	v_cvt_pk_bf16_f32 v103, v103, s0
	v_mul_f32_e32 v102, v102, v110
	ds_write_b16 v27, v103 offset:5472
	v_cvt_pk_bf16_f32 v102, v102, s0
	v_sub_f32_e32 v103, v105, v100
	ds_write_b16 v27, v102 offset:7776
	v_lshlrev_b32_e32 v102, 16, v99
	v_lshlrev_b32_e32 v99, 16, v101
	v_fma_f32 v105, v9, v103, v100
	v_sub_f32_e32 v103, v104, v99
	v_mul_f32_e32 v104, v14, v105
	ds_write_b16 v27, v106 offset:3168
	v_fma_f32 v106, v12, v103, v99
	v_rcp_f32_e32 v103, v98
	v_mul_f32_e32 v98, v104, v104
	v_sub_f32_e32 v101, v108, v102
	v_cvt_pk_bf16_f32 v109, v109, s0
	v_mov_b32_dpp v98, v98 quad_perm:[1,0,3,2] row_mask:0xf bank_mask:0xf bound_ctrl:1
	v_fmac_f32_e32 v98, v104, v104
	v_fma_f32 v101, v10, v101, v102
	v_lshlrev_b32_e32 v109, 16, v109
	v_add_f32_dpp v98, v98, v98 quad_perm:[2,3,0,1] row_mask:0xf bank_mask:0xf bound_ctrl:1
	v_cvt_pk_bf16_f32 v101, v101, s0
	v_mul_f32_e32 v107, v107, v109
	v_add_f32_dpp v98, v98, v98 row_ror:4 row_mask:0xf bank_mask:0xf bound_ctrl:1
	v_lshlrev_b32_e32 v101, 16, v101
	v_cvt_pk_bf16_f32 v107, v107, s0
	v_add_f32_dpp v98, v98, v98 row_ror:8 row_mask:0xf bank_mask:0xf bound_ctrl:1
	ds_write_b16 v27, v107 offset:864
	v_readlane_b32 s7, v98, 0
	v_readlane_b32 s8, v98, 16
	v_readlane_b32 s6, v98, 32
	v_readlane_b32 s9, v98, 48
	v_add_f32_e32 v98, -1.0, v103
	v_fma_f32 v98, v13, v98, 1.0
	v_mul_f32_e32 v98, v105, v98
	v_cvt_pk_bf16_f32 v98, v98, s0
	v_lshlrev_b32_e32 v98, 16, v98
	v_mul_f32_e32 v105, v101, v98
	v_mul_f32_e32 v107, v11, v105
	s_nop 1
	v_mov_b32_dpp v107, v107 quad_perm:[1,0,3,2] row_mask:0xf bank_mask:0xf bound_ctrl:1
	v_fmac_f32_e32 v107, v11, v105
	s_nop 1
	v_add_f32_dpp v105, v107, v107 quad_perm:[2,3,0,1] row_mask:0xf bank_mask:0xf bound_ctrl:1
	s_nop 1
	v_add_f32_dpp v105, v105, v105 row_ror:4 row_mask:0xf bank_mask:0xf bound_ctrl:1
	s_nop 1
	v_add_f32_dpp v105, v105, v105 row_ror:8 row_mask:0xf bank_mask:0xf bound_ctrl:1
	s_nop 0
	v_readlane_b32 s0, v105, 0
	v_readlane_b32 s15, v105, 16
	v_readlane_b32 s1, v105, 32
	v_readlane_b32 s17, v105, 48
	v_cvt_pk_bf16_f32 v105, v106, s0
	global_store_short v[156:157], v105, off offset:896
	s_and_saveexec_b64 s[4:5], s[38:39]
	s_cbranch_execz .LBB0_297
	s_ashr_i32 s65, s64, 31
	s_lshl_b64 s[30:31], s[64:65], 6
	s_add_u32 s30, s2, s30
	v_mov_b32_e32 v106, s15
	v_mov_b32_e32 v107, s17
	s_addc_u32 s31, s14, s31
	v_pk_add_f32 v[106:107], s[0:1], v[106:107]
	s_nop 0
	v_add_f32_e32 v105, v106, v107
	v_mov_b64_e32 v[106:107], s[30:31]
	global_store_dword v[106:107], v105, off
; __device__ __forceinline__ float bf2f(bf16 b) { return __uint_as_float((unsigned)b << 16); }
; __device__ __forceinline__ bf16 f2bf(float f) { return (bf16)(pk_bf16(f, 0.f) & 0xffffu); }
; __device__ __forceinline__ float fexp(float x) { return __builtin_amdgcn_exp2f(x * 1.4426950408889634f); }
; __device__ __forceinline__ float flog(float x) { return __builtin_amdgcn_logf(x) * 0.6931471805599453f; }
; __device__ __forceinline__ float fsigmoid(float x) { return __builtin_amdgcn_rcpf(1.0f + fexp(-x)); }
; __device__ __forceinline__ void pc_phase(LAS unsigned char* lds, const bf16* Pp_, const bf16* LO, const float* mu, const float* w0, const float* a0, const float* k_k, const float* k_a, const float* r_k, ...
;     ...
;         for (int t = 0; t < 16; ++t) {
;             const float r0 = bf2f(sr_[t + 1]), k0 = bf2f(sk_[t + 1]), v0 = bf2f(sv_[t + 1]);
;             const float r = r0 + (r1 - r0) * mu_r, k = k0 + (k1 - k0) * mu_k, v = v0 + (v1 - v0) * mu_v; r1 = r0; k1 = k0; v1 = v0;
;             const float z = -(w0c + bf2f(slw[t])); const float sp = fmaxf(z, 0.f) + flog(1.0f + fexp(-fabsf(z))); const float w = -sp - 0.5f;
;             const float dec = fexp(-fexp(w)); const float a = fsigmoid(a0c + bf2f(sla[t]));
;             float kk = k * kkc; const float n2 = wsum_dpp(kk * kk); kk = kk / fmaxf(sqrtf(n2), 1e-12f);
;             const float kp = bf2f(f2bf(k * (1.0f + (a - 1.0f) * kac))), bb = bf2f(f2bf(kk * a)), rr = bf2f(f2bf(r)); kk = bf2f(f2bf(kk));
;             const float coef = wsum_dpp(rr * kp * rkc);
;             SV[(ib + t) * 64 + lane] = f2bf(v);
;             if (lane == 0) COEF[(size_t)(m0 + t) * 16 + h] = coef;
;             const float Pp = P; P *= dec; const float inv = 1.0f / P;
;             XKK[t * 72 + lane] = f2bf(kk * Pp); XR[t * 72 + lane] = f2bf(rr * P); XK[t * 72 + lane] = f2bf(kp * inv); XB[t * 72 + lane] = f2bf(bb * inv); }
.LBB0_297:
	s_or_b64 exec, exec, s[4:5]
	v_lshlrev_b32_e32 v95, 16, v95
	v_add_f32_e32 v95, v8, v95
	v_mul_f32_e64 v105, |v95|, s19
	v_exp_f32_e32 v105, v105
	v_mov_b32_e32 v106, s8
	v_mov_b32_e32 v107, s9
	v_add_f32_e32 v106, s7, v106
	v_add_f32_e32 v105, 1.0, v105
	v_log_f32_e32 v105, v105
	v_add_f32_e32 v107, s6, v107
	v_max_f32_e64 v95, -v95, 0
	v_add_f32_e32 v106, v106, v107
	v_fmac_f32_e32 v95, 0x3f317218, v105
	v_mul_f32_e32 v105, 0x4f800000, v106
	v_cmp_gt_f32_e32 vcc, s33, v106
	v_sub_f32_e32 v95, -0.5, v95
	v_mul_f32_e32 v95, 0x3fb8aa3b, v95
	v_cndmask_b32_e32 v105, v106, v105, vcc
	v_sqrt_f32_e32 v106, v105
	v_exp_f32_e32 v95, v95
	v_lshlrev_b32_e32 v91, 16, v91
	v_add_f32_e32 v91, v15, v91
	v_add_u32_e32 v107, -1, v106
	v_fma_f32 v108, -v107, v106, v105
	v_cmp_ge_f32_e64 s[56:57], 0, v108
	v_add_u32_e32 v108, 1, v106
	v_mul_f32_e32 v95, 0xbfb8aa3b, v95
	v_cndmask_b32_e64 v107, v106, v107, s[56:57]
	v_fma_f32 v106, -v108, v106, v105
	v_cmp_lt_f32_e64 s[56:57], 0, v106
	v_exp_f32_e32 v95, v95
	v_mul_f32_e32 v91, 0xbfb8aa3b, v91
	v_cndmask_b32_e64 v106, v107, v108, s[56:57]
	v_mul_f32_e32 v107, 0x37800000, v106
	v_cndmask_b32_e32 v106, v106, v107, vcc
	v_cmp_class_f32_e32 vcc, v105, v219
	v_mul_f32_e32 v95, v96, v95
	v_exp_f32_e32 v91, v91
	v_cndmask_b32_e32 v105, v106, v105, vcc
	v_max_f32_e32 v105, 0x2b8cbccc, v105
	v_div_scale_f32 v106, s[0:1], v105, v105, v104
	v_rcp_f32_e32 v107, v106
	v_lshlrev_b32_e32 v93, 16, v93
	v_add_f32_e32 v91, 1.0, v91
	v_fma_f32 v108, -v106, v107, 1.0
	v_fmac_f32_e32 v107, v108, v107
	v_div_scale_f32 v108, vcc, v104, v105, v104
	v_mul_f32_e32 v109, v108, v107
	v_fma_f32 v110, -v106, v109, v108
	v_fmac_f32_e32 v109, v110, v107
	v_fma_f32 v106, -v106, v109, v108
	v_div_fmas_f32 v106, v106, v107, v109
	v_div_fixup_f32 v104, v106, v105, v104
	v_mul_f32_e32 v103, v103, v104
	v_cvt_pk_bf16_f32 v103, v103, s0
	v_div_scale_f32 v105, s[0:1], v95, v95, 1.0
	v_rcp_f32_e32 v106, v105
	s_nop 0
	v_cvt_pk_bf16_f32 v104, v104, s0
	v_lshlrev_b32_e32 v104, 16, v104
	v_mul_f32_e32 v96, v96, v104
	v_fma_f32 v107, -v105, v106, 1.0
	v_fmac_f32_e32 v106, v107, v106
	v_div_scale_f32 v107, vcc, 1.0, v95, 1.0
	v_mul_f32_e32 v108, v107, v106
	v_fma_f32 v109, -v105, v108, v107
	v_fmac_f32_e32 v108, v109, v106
	v_fma_f32 v105, -v105, v108, v107
	v_cvt_pk_bf16_f32 v96, v96, s0
	v_div_fmas_f32 v105, v105, v106, v108
	ds_write_b16 v27, v96 offset:1008
	v_mul_f32_e32 v96, v95, v101
	v_div_fixup_f32 v105, v105, v95, 1.0
	v_cvt_pk_bf16_f32 v96, v96, s0
	ds_write_b16 v27, v96 offset:3312
	v_mul_f32_e32 v96, v105, v98
	v_lshlrev_b32_e32 v103, 16, v103
	v_cvt_pk_bf16_f32 v96, v96, s0
	ds_write_b16 v27, v96 offset:5616
	v_mul_f32_e32 v96, v105, v103
	v_cvt_pk_bf16_f32 v96, v96, s0
	v_sub_f32_e32 v98, v100, v93
	ds_write_b16 v27, v96 offset:7920
	v_lshlrev_b32_e32 v96, 16, v92
	v_lshlrev_b32_e32 v92, 16, v94
	v_fma_f32 v100, v9, v98, v93
	v_sub_f32_e32 v98, v99, v92
	v_mul_f32_e32 v99, v14, v100
	v_fma_f32 v101, v12, v98, v92
	v_rcp_f32_e32 v98, v91
	v_mul_f32_e32 v91, v99, v99
	v_sub_f32_e32 v94, v102, v96
	v_fma_f32 v94, v10, v94, v96
	v_mov_b32_dpp v91, v91 quad_perm:[1,0,3,2] row_mask:0xf bank_mask:0xf bound_ctrl:1
	v_fmac_f32_e32 v91, v99, v99
	v_cvt_pk_bf16_f32 v94, v94, s0
	v_lshlrev_b32_e32 v94, 16, v94
	v_add_f32_dpp v91, v91, v91 quad_perm:[2,3,0,1] row_mask:0xf bank_mask:0xf bound_ctrl:1
	s_nop 1
	v_add_f32_dpp v91, v91, v91 row_ror:4 row_mask:0xf bank_mask:0xf bound_ctrl:1
	s_nop 1
	v_add_f32_dpp v91, v91, v91 row_ror:8 row_mask:0xf bank_mask:0xf bound_ctrl:1
	s_nop 0
	v_readlane_b32 s7, v91, 0
	v_readlane_b32 s8, v91, 16
	v_readlane_b32 s6, v91, 32
	v_readlane_b32 s9, v91, 48
	v_add_f32_e32 v91, -1.0, v98
	v_fma_f32 v91, v13, v91, 1.0
	v_mul_f32_e32 v91, v100, v91
	v_cvt_pk_bf16_f32 v91, v91, s0
	v_lshlrev_b32_e32 v91, 16, v91
	v_mul_f32_e32 v100, v94, v91
	v_mul_f32_e32 v102, v11, v100
	s_nop 1
	v_mov_b32_dpp v102, v102 quad_perm:[1,0,3,2] row_mask:0xf bank_mask:0xf bound_ctrl:1
	v_fmac_f32_e32 v102, v11, v100
	s_nop 1
	v_add_f32_dpp v100, v102, v102 quad_perm:[2,3,0,1] row_mask:0xf bank_mask:0xf bound_ctrl:1
	s_nop 1
	v_add_f32_dpp v100, v100, v100 row_ror:4 row_mask:0xf bank_mask:0xf bound_ctrl:1
	s_nop 1
	v_add_f32_dpp v100, v100, v100 row_ror:8 row_mask:0xf bank_mask:0xf bound_ctrl:1
	s_nop 0
	v_readlane_b32 s0, v100, 0
	v_readlane_b32 s15, v100, 16
	v_readlane_b32 s1, v100, 32
	v_readlane_b32 s17, v100, 48
	v_cvt_pk_bf16_f32 v102, v101, s0
	global_store_short v[156:157], v102, off offset:1024
	s_and_saveexec_b64 s[4:5], s[38:39]
	s_cbranch_execz .LBB0_299
	s_ashr_i32 s63, s62, 31
	s_lshl_b64 s[30:31], s[62:63], 6
	s_add_u32 s30, s2, s30
	v_mov_b32_e32 v100, s15
	v_mov_b32_e32 v101, s17
	s_addc_u32 s31, s14, s31
	v_pk_add_f32 v[100:101], s[0:1], v[100:101]
	v_readlane_b32 s63, v254, 44
	v_add_f32_e32 v102, v100, v101
	v_mov_b64_e32 v[100:101], s[30:31]
	global_store_dword v[100:101], v102, off
; __device__ __forceinline__ float bf2f(bf16 b) { return __uint_as_float((unsigned)b << 16); }
; __device__ __forceinline__ bf16 f2bf(float f) { return (bf16)(pk_bf16(f, 0.f) & 0xffffu); }
; __device__ __forceinline__ float fexp(float x) { return __builtin_amdgcn_exp2f(x * 1.4426950408889634f); }
; __device__ __forceinline__ float flog(float x) { return __builtin_amdgcn_logf(x) * 0.6931471805599453f; }
; __device__ __forceinline__ float fsigmoid(float x) { return __builtin_amdgcn_rcpf(1.0f + fexp(-x)); }
; __device__ __forceinline__ void pc_phase(LAS unsigned char* lds, const bf16* Pp_, const bf16* LO, const float* mu, const float* w0, const float* a0, const float* k_k, const float* k_a, const float* r_k, ...
;     ...
;         for (int t = 0; t < 16; ++t) {
;             const float r0 = bf2f(sr_[t + 1]), k0 = bf2f(sk_[t + 1]), v0 = bf2f(sv_[t + 1]);
;             const float r = r0 + (r1 - r0) * mu_r, k = k0 + (k1 - k0) * mu_k, v = v0 + (v1 - v0) * mu_v; r1 = r0; k1 = k0; v1 = v0;
;             const float z = -(w0c + bf2f(slw[t])); const float sp = fmaxf(z, 0.f) + flog(1.0f + fexp(-fabsf(z))); const float w = -sp - 0.5f;
;             const float dec = fexp(-fexp(w)); const float a = fsigmoid(a0c + bf2f(sla[t]));
;             float kk = k * kkc; const float n2 = wsum_dpp(kk * kk); kk = kk / fmaxf(sqrtf(n2), 1e-12f);
;             const float kp = bf2f(f2bf(k * (1.0f + (a - 1.0f) * kac))), bb = bf2f(f2bf(kk * a)), rr = bf2f(f2bf(r)); kk = bf2f(f2bf(kk));
;             const float coef = wsum_dpp(rr * kp * rkc);
;             SV[(ib + t) * 64 + lane] = f2bf(v);
;             if (lane == 0) COEF[(size_t)(m0 + t) * 16 + h] = coef;
;             const float Pp = P; P *= dec; const float inv = 1.0f / P;
;             XKK[t * 72 + lane] = f2bf(kk * Pp); XR[t * 72 + lane] = f2bf(rr * P); XK[t * 72 + lane] = f2bf(kp * inv); XB[t * 72 + lane] = f2bf(bb * inv); }
.LBB0_299:
	s_or_b64 exec, exec, s[4:5]
	v_lshlrev_b32_e32 v90, 16, v90
	v_add_f32_e32 v90, v8, v90
	v_mul_f32_e64 v100, |v90|, s19
	v_exp_f32_e32 v100, v100
	v_mov_b32_e32 v101, s8
	v_mov_b32_e32 v102, s9
	v_add_f32_e32 v101, s7, v101
	v_add_f32_e32 v100, 1.0, v100
	v_log_f32_e32 v100, v100
	v_add_f32_e32 v102, s6, v102
	v_max_f32_e64 v90, -v90, 0
	v_add_f32_e32 v101, v101, v102
	v_fmac_f32_e32 v90, 0x3f317218, v100
	v_mul_f32_e32 v100, 0x4f800000, v101
	v_cmp_gt_f32_e32 vcc, s33, v101
	v_sub_f32_e32 v90, -0.5, v90
	v_mul_f32_e32 v90, 0x3fb8aa3b, v90
	v_cndmask_b32_e32 v100, v101, v100, vcc
	v_sqrt_f32_e32 v101, v100
	v_exp_f32_e32 v90, v90
	v_lshlrev_b32_e32 v86, 16, v86
	v_add_f32_e32 v86, v15, v86
	v_add_u32_e32 v102, -1, v101
	v_fma_f32 v103, -v102, v101, v100
	v_cmp_ge_f32_e64 s[56:57], 0, v103
	v_add_u32_e32 v103, 1, v101
	v_mul_f32_e32 v90, 0xbfb8aa3b, v90
	v_cndmask_b32_e64 v102, v101, v102, s[56:57]
	v_fma_f32 v101, -v103, v101, v100
	v_cmp_lt_f32_e64 s[56:57], 0, v101
	v_exp_f32_e32 v90, v90
	v_mul_f32_e32 v86, 0xbfb8aa3b, v86
	v_cndmask_b32_e64 v101, v102, v103, s[56:57]
	v_mul_f32_e32 v102, 0x37800000, v101
	v_cndmask_b32_e32 v101, v101, v102, vcc
	v_cmp_class_f32_e32 vcc, v100, v219
	v_mul_f32_e32 v90, v95, v90
	v_exp_f32_e32 v86, v86
	v_cndmask_b32_e32 v100, v101, v100, vcc
	v_max_f32_e32 v100, 0x2b8cbccc, v100
	v_div_scale_f32 v101, s[0:1], v100, v100, v99
	v_rcp_f32_e32 v102, v101
	v_mul_f32_e32 v94, v90, v94
	v_lshlrev_b32_e32 v88, 16, v88
	v_sub_f32_e32 v93, v93, v88
	v_fma_f32 v103, -v101, v102, 1.0
	v_fmac_f32_e32 v102, v103, v102
	v_div_scale_f32 v103, vcc, v99, v100, v99
	v_mul_f32_e32 v104, v103, v102
	v_fma_f32 v105, -v101, v104, v103
	v_fmac_f32_e32 v104, v105, v102
	v_fma_f32 v101, -v101, v104, v103
	v_div_fmas_f32 v101, v101, v102, v104
	v_div_fixup_f32 v99, v101, v100, v99
	v_mul_f32_e32 v98, v98, v99
	v_cvt_pk_bf16_f32 v98, v98, s0
	v_div_scale_f32 v100, s[0:1], v90, v90, 1.0
	v_rcp_f32_e32 v101, v100
	v_lshlrev_b32_e32 v98, 16, v98
	v_cvt_pk_bf16_f32 v99, v99, s0
	v_lshlrev_b32_e32 v99, 16, v99
	v_fma_f32 v102, -v100, v101, 1.0
	v_fmac_f32_e32 v101, v102, v101
	v_div_scale_f32 v102, vcc, 1.0, v90, 1.0
	v_mul_f32_e32 v103, v102, v101
	v_fma_f32 v104, -v100, v103, v102
	v_fmac_f32_e32 v103, v104, v101
	v_fma_f32 v100, -v100, v103, v102
	v_div_fmas_f32 v100, v100, v101, v103
	v_div_fixup_f32 v100, v100, v90, 1.0
	v_mul_f32_e32 v91, v100, v91
	v_cvt_pk_bf16_f32 v91, v91, s0
	ds_write_b16 v27, v91 offset:5760
	v_mul_f32_e32 v91, v100, v98
	v_cvt_pk_bf16_f32 v94, v94, s0
	v_cvt_pk_bf16_f32 v91, v91, s0
	v_mul_f32_e32 v95, v95, v99
	ds_write_b16 v27, v94 offset:3456
	ds_write_b16 v27, v91 offset:8064
	v_lshlrev_b32_e32 v91, 16, v87
	v_lshlrev_b32_e32 v87, 16, v89
	v_fma_f32 v94, v9, v93, v88
	v_cvt_pk_bf16_f32 v95, v95, s0
	v_sub_f32_e32 v92, v92, v87
	v_add_f32_e32 v86, 1.0, v86
	v_mul_f32_e32 v93, v14, v94
	ds_write_b16 v27, v95 offset:1152
	v_fma_f32 v95, v12, v92, v87
	v_rcp_f32_e32 v92, v86
	v_mul_f32_e32 v86, v93, v93
	v_sub_f32_e32 v89, v96, v91
	v_fma_f32 v89, v10, v89, v91
	v_mov_b32_dpp v86, v86 quad_perm:[1,0,3,2] row_mask:0xf bank_mask:0xf bound_ctrl:1
	v_fmac_f32_e32 v86, v93, v93
	v_cvt_pk_bf16_f32 v89, v89, s0
	v_lshlrev_b32_e32 v89, 16, v89
	v_add_f32_dpp v86, v86, v86 quad_perm:[2,3,0,1] row_mask:0xf bank_mask:0xf bound_ctrl:1
	s_nop 1
	v_add_f32_dpp v86, v86, v86 row_ror:4 row_mask:0xf bank_mask:0xf bound_ctrl:1
	s_nop 1
	v_add_f32_dpp v86, v86, v86 row_ror:8 row_mask:0xf bank_mask:0xf bound_ctrl:1
	s_nop 0
	v_readlane_b32 s7, v86, 0
	v_readlane_b32 s8, v86, 16
	v_readlane_b32 s6, v86, 32
	v_readlane_b32 s9, v86, 48
	v_add_f32_e32 v86, -1.0, v92
	v_fma_f32 v86, v13, v86, 1.0
	v_mul_f32_e32 v86, v94, v86
	v_cvt_pk_bf16_f32 v86, v86, s0
	v_lshlrev_b32_e32 v86, 16, v86
	v_mul_f32_e32 v94, v89, v86
	v_mul_f32_e32 v96, v11, v94
	s_nop 1
	v_mov_b32_dpp v96, v96 quad_perm:[1,0,3,2] row_mask:0xf bank_mask:0xf bound_ctrl:1
	v_fmac_f32_e32 v96, v11, v94
	s_nop 1
	v_add_f32_dpp v94, v96, v96 quad_perm:[2,3,0,1] row_mask:0xf bank_mask:0xf bound_ctrl:1
	s_nop 1
	v_add_f32_dpp v94, v94, v94 row_ror:4 row_mask:0xf bank_mask:0xf bound_ctrl:1
	s_nop 1
	v_add_f32_dpp v94, v94, v94 row_ror:8 row_mask:0xf bank_mask:0xf bound_ctrl:1
	s_nop 0
	v_readlane_b32 s0, v94, 0
	v_readlane_b32 s15, v94, 16
	v_readlane_b32 s1, v94, 32
	v_readlane_b32 s17, v94, 48
	v_cvt_pk_bf16_f32 v96, v95, s0
	global_store_short v[156:157], v96, off offset:1152
	s_and_saveexec_b64 s[4:5], s[38:39]
	s_cbranch_execz .LBB0_301
	s_ashr_i32 s37, s36, 31
	s_lshl_b64 s[30:31], s[36:37], 6
	s_add_u32 s30, s2, s30
	v_mov_b32_e32 v94, s15
	v_mov_b32_e32 v95, s17
	s_addc_u32 s31, s14, s31
	v_pk_add_f32 v[94:95], s[0:1], v[94:95]
	s_nop 0
	v_add_f32_e32 v96, v94, v95
	v_mov_b64_e32 v[94:95], s[30:31]
	global_store_dword v[94:95], v96, off
; __device__ __forceinline__ float bf2f(bf16 b) { return __uint_as_float((unsigned)b << 16); }
; __device__ __forceinline__ bf16 f2bf(float f) { return (bf16)(pk_bf16(f, 0.f) & 0xffffu); }
; __device__ __forceinline__ float fexp(float x) { return __builtin_amdgcn_exp2f(x * 1.4426950408889634f); }
; __device__ __forceinline__ float flog(float x) { return __builtin_amdgcn_logf(x) * 0.6931471805599453f; }
; __device__ __forceinline__ float fsigmoid(float x) { return __builtin_amdgcn_rcpf(1.0f + fexp(-x)); }
; __device__ __forceinline__ void pc_phase(LAS unsigned char* lds, const bf16* Pp_, const bf16* LO, const float* mu, const float* w0, const float* a0, const float* k_k, const float* k_a, const float* r_k, ...
;     ...
;         for (int t = 0; t < 16; ++t) {
;             const float r0 = bf2f(sr_[t + 1]), k0 = bf2f(sk_[t + 1]), v0 = bf2f(sv_[t + 1]);
;             const float r = r0 + (r1 - r0) * mu_r, k = k0 + (k1 - k0) * mu_k, v = v0 + (v1 - v0) * mu_v; r1 = r0; k1 = k0; v1 = v0;
;             const float z = -(w0c + bf2f(slw[t])); const float sp = fmaxf(z, 0.f) + flog(1.0f + fexp(-fabsf(z))); const float w = -sp - 0.5f;
;             const float dec = fexp(-fexp(w)); const float a = fsigmoid(a0c + bf2f(sla[t]));
;             float kk = k * kkc; const float n2 = wsum_dpp(kk * kk); kk = kk / fmaxf(sqrtf(n2), 1e-12f);
;             const float kp = bf2f(f2bf(k * (1.0f + (a - 1.0f) * kac))), bb = bf2f(f2bf(kk * a)), rr = bf2f(f2bf(r)); kk = bf2f(f2bf(kk));
;             const float coef = wsum_dpp(rr * kp * rkc);
;             SV[(ib + t) * 64 + lane] = f2bf(v);
;             if (lane == 0) COEF[(size_t)(m0 + t) * 16 + h] = coef;
;             const float Pp = P; P *= dec; const float inv = 1.0f / P;
;             XKK[t * 72 + lane] = f2bf(kk * Pp); XR[t * 72 + lane] = f2bf(rr * P); XK[t * 72 + lane] = f2bf(kp * inv); XB[t * 72 + lane] = f2bf(bb * inv); }
.LBB0_301:
	s_or_b64 exec, exec, s[4:5]
	v_lshlrev_b32_e32 v85, 16, v85
	v_add_f32_e32 v85, v8, v85
	v_mul_f32_e64 v94, |v85|, s19
	v_exp_f32_e32 v94, v94
	v_mov_b32_e32 v95, s8
	v_mov_b32_e32 v96, s9
	v_add_f32_e32 v95, s7, v95
	v_add_f32_e32 v94, 1.0, v94
	v_log_f32_e32 v94, v94
	v_add_f32_e32 v96, s6, v96
	v_max_f32_e64 v85, -v85, 0
	v_add_f32_e32 v95, v95, v96
	v_fmac_f32_e32 v85, 0x3f317218, v94
	v_mul_f32_e32 v94, 0x4f800000, v95
	v_cmp_gt_f32_e32 vcc, s33, v95
	v_sub_f32_e32 v85, -0.5, v85
	v_mul_f32_e32 v85, 0x3fb8aa3b, v85
	v_cndmask_b32_e32 v94, v95, v94, vcc
	v_sqrt_f32_e32 v95, v94
	v_exp_f32_e32 v85, v85
	v_lshlrev_b32_e32 v81, 16, v81
	v_add_f32_e32 v81, v15, v81
	v_add_u32_e32 v96, -1, v95
	v_fma_f32 v98, -v96, v95, v94
	v_cmp_ge_f32_e64 s[56:57], 0, v98
	v_add_u32_e32 v98, 1, v95
	v_mul_f32_e32 v85, 0xbfb8aa3b, v85
	v_cndmask_b32_e64 v96, v95, v96, s[56:57]
	v_fma_f32 v95, -v98, v95, v94
	v_cmp_lt_f32_e64 s[56:57], 0, v95
	v_exp_f32_e32 v85, v85
	v_mul_f32_e32 v81, 0xbfb8aa3b, v81
	v_cndmask_b32_e64 v95, v96, v98, s[56:57]
	v_mul_f32_e32 v96, 0x37800000, v95
	v_cndmask_b32_e32 v95, v95, v96, vcc
	v_cmp_class_f32_e32 vcc, v94, v219
	v_mul_f32_e32 v85, v90, v85
	v_exp_f32_e32 v81, v81
	v_cndmask_b32_e32 v94, v95, v94, vcc
	v_max_f32_e32 v94, 0x2b8cbccc, v94
	v_div_scale_f32 v95, s[0:1], v94, v94, v93
	v_rcp_f32_e32 v96, v95
	v_mul_f32_e32 v89, v85, v89
	v_lshlrev_b32_e32 v83, 16, v83
	v_sub_f32_e32 v88, v88, v83
	v_fma_f32 v98, -v95, v96, 1.0
	v_fmac_f32_e32 v96, v98, v96
	v_div_scale_f32 v98, vcc, v93, v94, v93
	v_mul_f32_e32 v99, v98, v96
	v_fma_f32 v100, -v95, v99, v98
	v_fmac_f32_e32 v99, v100, v96
	v_fma_f32 v95, -v95, v99, v98
	v_div_fmas_f32 v95, v95, v96, v99
	v_div_fixup_f32 v93, v95, v94, v93
	v_mul_f32_e32 v92, v92, v93
	v_cvt_pk_bf16_f32 v92, v92, s0
	v_div_scale_f32 v94, s[0:1], v85, v85, 1.0
	v_rcp_f32_e32 v95, v94
	v_lshlrev_b32_e32 v92, 16, v92
	v_cvt_pk_bf16_f32 v93, v93, s0
	v_lshlrev_b32_e32 v93, 16, v93
	v_fma_f32 v96, -v94, v95, 1.0
	v_fmac_f32_e32 v95, v96, v95
	v_div_scale_f32 v96, vcc, 1.0, v85, 1.0
	v_mul_f32_e32 v98, v96, v95
	v_fma_f32 v99, -v94, v98, v96
	v_fmac_f32_e32 v98, v99, v95
	v_fma_f32 v94, -v94, v98, v96
	v_div_fmas_f32 v94, v94, v95, v98
	v_div_fixup_f32 v94, v94, v85, 1.0
	v_mul_f32_e32 v86, v94, v86
	v_cvt_pk_bf16_f32 v86, v86, s0
	ds_write_b16 v27, v86 offset:5904
	v_mul_f32_e32 v86, v94, v92
	v_cvt_pk_bf16_f32 v89, v89, s0
	v_cvt_pk_bf16_f32 v86, v86, s0
	v_mul_f32_e32 v90, v90, v93
	ds_write_b16 v27, v89 offset:3600
	ds_write_b16 v27, v86 offset:8208
	v_lshlrev_b32_e32 v86, 16, v82
	v_lshlrev_b32_e32 v82, 16, v84
	v_fma_f32 v89, v9, v88, v83
	v_cvt_pk_bf16_f32 v90, v90, s0
	v_sub_f32_e32 v87, v87, v82
	v_add_f32_e32 v81, 1.0, v81
	v_mul_f32_e32 v88, v14, v89
	ds_write_b16 v27, v90 offset:1296
	v_fma_f32 v90, v12, v87, v82
	v_rcp_f32_e32 v87, v81
	v_mul_f32_e32 v81, v88, v88
	v_sub_f32_e32 v84, v91, v86
	v_fma_f32 v84, v10, v84, v86
	v_mov_b32_dpp v81, v81 quad_perm:[1,0,3,2] row_mask:0xf bank_mask:0xf bound_ctrl:1
	v_fmac_f32_e32 v81, v88, v88
	v_cvt_pk_bf16_f32 v84, v84, s0
	v_lshlrev_b32_e32 v84, 16, v84
	v_add_f32_dpp v81, v81, v81 quad_perm:[2,3,0,1] row_mask:0xf bank_mask:0xf bound_ctrl:1
	s_nop 1
	v_add_f32_dpp v81, v81, v81 row_ror:4 row_mask:0xf bank_mask:0xf bound_ctrl:1
	s_nop 1
	v_add_f32_dpp v81, v81, v81 row_ror:8 row_mask:0xf bank_mask:0xf bound_ctrl:1
	s_nop 0
	v_readlane_b32 s7, v81, 0
	v_readlane_b32 s8, v81, 16
	v_readlane_b32 s6, v81, 32
	v_readlane_b32 s9, v81, 48
	v_add_f32_e32 v81, -1.0, v87
	v_fma_f32 v81, v13, v81, 1.0
	v_mul_f32_e32 v81, v89, v81
	v_cvt_pk_bf16_f32 v81, v81, s0
	v_lshlrev_b32_e32 v81, 16, v81
	v_mul_f32_e32 v89, v84, v81
	v_mul_f32_e32 v91, v11, v89
	s_nop 1
	v_mov_b32_dpp v91, v91 quad_perm:[1,0,3,2] row_mask:0xf bank_mask:0xf bound_ctrl:1
	v_fmac_f32_e32 v91, v11, v89
	s_nop 1
	v_add_f32_dpp v89, v91, v91 quad_perm:[2,3,0,1] row_mask:0xf bank_mask:0xf bound_ctrl:1
	s_nop 1
	v_add_f32_dpp v89, v89, v89 row_ror:4 row_mask:0xf bank_mask:0xf bound_ctrl:1
	s_nop 1
	v_add_f32_dpp v89, v89, v89 row_ror:8 row_mask:0xf bank_mask:0xf bound_ctrl:1
	s_nop 0
	v_readlane_b32 s0, v89, 0
	v_readlane_b32 s15, v89, 16
	v_readlane_b32 s1, v89, 32
	v_readlane_b32 s17, v89, 48
	v_cvt_pk_bf16_f32 v89, v90, s0
	global_store_short v[156:157], v89, off offset:1280
	s_and_saveexec_b64 s[4:5], s[38:39]
	s_cbranch_execz .LBB0_303
	s_ashr_i32 s85, s84, 31
	s_lshl_b64 s[30:31], s[84:85], 6
	s_add_u32 s30, s2, s30
	v_mov_b32_e32 v90, s15
	v_mov_b32_e32 v91, s17
	s_addc_u32 s31, s14, s31
	v_pk_add_f32 v[90:91], s[0:1], v[90:91]
	s_nop 0
	v_add_f32_e32 v89, v90, v91
	v_mov_b64_e32 v[90:91], s[30:31]
	global_store_dword v[90:91], v89, off
; __device__ __forceinline__ float bf2f(bf16 b) { return __uint_as_float((unsigned)b << 16); }
; __device__ __forceinline__ bf16 f2bf(float f) { return (bf16)(pk_bf16(f, 0.f) & 0xffffu); }
; __device__ __forceinline__ float fexp(float x) { return __builtin_amdgcn_exp2f(x * 1.4426950408889634f); }
; __device__ __forceinline__ float flog(float x) { return __builtin_amdgcn_logf(x) * 0.6931471805599453f; }
; __device__ __forceinline__ float fsigmoid(float x) { return __builtin_amdgcn_rcpf(1.0f + fexp(-x)); }
; __device__ __forceinline__ void pc_phase(LAS unsigned char* lds, const bf16* Pp_, const bf16* LO, const float* mu, const float* w0, const float* a0, const float* k_k, const float* k_a, const float* r_k, ...
;     ...
;         for (int t = 0; t < 16; ++t) {
;             const float r0 = bf2f(sr_[t + 1]), k0 = bf2f(sk_[t + 1]), v0 = bf2f(sv_[t + 1]);
;             const float r = r0 + (r1 - r0) * mu_r, k = k0 + (k1 - k0) * mu_k, v = v0 + (v1 - v0) * mu_v; r1 = r0; k1 = k0; v1 = v0;
;             const float z = -(w0c + bf2f(slw[t])); const float sp = fmaxf(z, 0.f) + flog(1.0f + fexp(-fabsf(z))); const float w = -sp - 0.5f;
;             const float dec = fexp(-fexp(w)); const float a = fsigmoid(a0c + bf2f(sla[t]));
;             float kk = k * kkc; const float n2 = wsum_dpp(kk * kk); kk = kk / fmaxf(sqrtf(n2), 1e-12f);
;             const float kp = bf2f(f2bf(k * (1.0f + (a - 1.0f) * kac))), bb = bf2f(f2bf(kk * a)), rr = bf2f(f2bf(r)); kk = bf2f(f2bf(kk));
;             const float coef = wsum_dpp(rr * kp * rkc);
;             SV[(ib + t) * 64 + lane] = f2bf(v);
;             if (lane == 0) COEF[(size_t)(m0 + t) * 16 + h] = coef;
;             const float Pp = P; P *= dec; const float inv = 1.0f / P;
;             XKK[t * 72 + lane] = f2bf(kk * Pp); XR[t * 72 + lane] = f2bf(rr * P); XK[t * 72 + lane] = f2bf(kp * inv); XB[t * 72 + lane] = f2bf(bb * inv); }
.LBB0_303:
	s_or_b64 exec, exec, s[4:5]
	v_lshlrev_b32_e32 v80, 16, v80
	v_add_f32_e32 v80, v8, v80
	v_mul_f32_e64 v89, |v80|, s19
	v_exp_f32_e32 v89, v89
	v_mov_b32_e32 v90, s8
	v_mov_b32_e32 v91, s9
	v_add_f32_e32 v90, s7, v90
	v_add_f32_e32 v89, 1.0, v89
	v_log_f32_e32 v89, v89
	v_add_f32_e32 v91, s6, v91
	v_max_f32_e64 v80, -v80, 0
	v_add_f32_e32 v90, v90, v91
	v_fmac_f32_e32 v80, 0x3f317218, v89
	v_mul_f32_e32 v89, 0x4f800000, v90
	v_cmp_gt_f32_e32 vcc, s33, v90
	v_sub_f32_e32 v80, -0.5, v80
	v_mul_f32_e32 v80, 0x3fb8aa3b, v80
	v_cndmask_b32_e32 v89, v90, v89, vcc
	v_sqrt_f32_e32 v90, v89
	v_exp_f32_e32 v80, v80
	v_lshlrev_b32_e32 v76, 16, v76
	v_add_f32_e32 v76, v15, v76
	v_add_u32_e32 v91, -1, v90
	v_fma_f32 v92, -v91, v90, v89
	v_cmp_ge_f32_e64 s[56:57], 0, v92
	v_add_u32_e32 v92, 1, v90
	v_mul_f32_e32 v80, 0xbfb8aa3b, v80
	v_cndmask_b32_e64 v91, v90, v91, s[56:57]
	v_fma_f32 v90, -v92, v90, v89
	v_cmp_lt_f32_e64 s[56:57], 0, v90
	v_exp_f32_e32 v80, v80
	v_mul_f32_e32 v76, 0xbfb8aa3b, v76
	v_cndmask_b32_e64 v90, v91, v92, s[56:57]
	v_mul_f32_e32 v91, 0x37800000, v90
	v_cndmask_b32_e32 v90, v90, v91, vcc
	v_cmp_class_f32_e32 vcc, v89, v219
	v_mul_f32_e32 v80, v85, v80
	v_exp_f32_e32 v76, v76
	v_cndmask_b32_e32 v89, v90, v89, vcc
	v_max_f32_e32 v89, 0x2b8cbccc, v89
	v_div_scale_f32 v90, s[0:1], v89, v89, v88
	v_rcp_f32_e32 v91, v90
	v_mul_f32_e32 v84, v80, v84
	v_lshlrev_b32_e32 v78, 16, v78
	v_sub_f32_e32 v83, v83, v78
	v_fma_f32 v92, -v90, v91, 1.0
	v_fmac_f32_e32 v91, v92, v91
	v_div_scale_f32 v92, vcc, v88, v89, v88
	v_mul_f32_e32 v93, v92, v91
	v_fma_f32 v94, -v90, v93, v92
	v_fmac_f32_e32 v93, v94, v91
	v_fma_f32 v90, -v90, v93, v92
	v_div_fmas_f32 v90, v90, v91, v93
	v_div_fixup_f32 v88, v90, v89, v88
	v_mul_f32_e32 v87, v87, v88
	v_cvt_pk_bf16_f32 v87, v87, s0
	v_div_scale_f32 v89, s[0:1], v80, v80, 1.0
	v_rcp_f32_e32 v90, v89
	v_lshlrev_b32_e32 v87, 16, v87
	v_cvt_pk_bf16_f32 v88, v88, s0
	v_lshlrev_b32_e32 v88, 16, v88
	v_fma_f32 v91, -v89, v90, 1.0
	v_fmac_f32_e32 v90, v91, v90
	v_div_scale_f32 v91, vcc, 1.0, v80, 1.0
	v_mul_f32_e32 v92, v91, v90
	v_fma_f32 v93, -v89, v92, v91
	v_fmac_f32_e32 v92, v93, v90
	v_fma_f32 v89, -v89, v92, v91
	v_div_fmas_f32 v89, v89, v90, v92
	v_div_fixup_f32 v89, v89, v80, 1.0
	v_mul_f32_e32 v81, v89, v81
	v_cvt_pk_bf16_f32 v81, v81, s0
	ds_write_b16 v27, v81 offset:6048
	v_mul_f32_e32 v81, v89, v87
	v_cvt_pk_bf16_f32 v84, v84, s0
	v_cvt_pk_bf16_f32 v81, v81, s0
	v_mul_f32_e32 v85, v85, v88
	ds_write_b16 v27, v84 offset:3744
	ds_write_b16 v27, v81 offset:8352
	v_lshlrev_b32_e32 v81, 16, v77
	v_lshlrev_b32_e32 v77, 16, v79
	v_fma_f32 v84, v9, v83, v78
	v_cvt_pk_bf16_f32 v85, v85, s0
	v_sub_f32_e32 v82, v82, v77
	v_add_f32_e32 v76, 1.0, v76
	v_mul_f32_e32 v83, v14, v84
	ds_write_b16 v27, v85 offset:1440
	v_fma_f32 v85, v12, v82, v77
	v_rcp_f32_e32 v82, v76
	v_mul_f32_e32 v76, v83, v83
	v_sub_f32_e32 v79, v86, v81
	v_fma_f32 v79, v10, v79, v81
	v_mov_b32_dpp v76, v76 quad_perm:[1,0,3,2] row_mask:0xf bank_mask:0xf bound_ctrl:1
	v_fmac_f32_e32 v76, v83, v83
	v_cvt_pk_bf16_f32 v79, v79, s0
	v_lshlrev_b32_e32 v79, 16, v79
	v_add_f32_dpp v76, v76, v76 quad_perm:[2,3,0,1] row_mask:0xf bank_mask:0xf bound_ctrl:1
	s_nop 1
	v_add_f32_dpp v76, v76, v76 row_ror:4 row_mask:0xf bank_mask:0xf bound_ctrl:1
	s_nop 1
	v_add_f32_dpp v76, v76, v76 row_ror:8 row_mask:0xf bank_mask:0xf bound_ctrl:1
	s_nop 0
	v_readlane_b32 s7, v76, 0
	v_readlane_b32 s8, v76, 16
	v_readlane_b32 s6, v76, 32
	v_readlane_b32 s9, v76, 48
	v_add_f32_e32 v76, -1.0, v82
	v_fma_f32 v76, v13, v76, 1.0
	v_mul_f32_e32 v76, v84, v76
	v_cvt_pk_bf16_f32 v76, v76, s0
	v_lshlrev_b32_e32 v76, 16, v76
	v_mul_f32_e32 v84, v79, v76
	v_mul_f32_e32 v86, v11, v84
	s_nop 1
	v_mov_b32_dpp v86, v86 quad_perm:[1,0,3,2] row_mask:0xf bank_mask:0xf bound_ctrl:1
	v_fmac_f32_e32 v86, v11, v84
	s_nop 1
	v_add_f32_dpp v84, v86, v86 quad_perm:[2,3,0,1] row_mask:0xf bank_mask:0xf bound_ctrl:1
	s_nop 1
	v_add_f32_dpp v84, v84, v84 row_ror:4 row_mask:0xf bank_mask:0xf bound_ctrl:1
	s_nop 1
	v_add_f32_dpp v84, v84, v84 row_ror:8 row_mask:0xf bank_mask:0xf bound_ctrl:1
	s_nop 0
	v_readlane_b32 s0, v84, 0
	v_readlane_b32 s15, v84, 16
	v_readlane_b32 s1, v84, 32
	v_readlane_b32 s17, v84, 48
	v_cvt_pk_bf16_f32 v86, v85, s0
	global_store_short v[156:157], v86, off offset:1408
	s_and_saveexec_b64 s[4:5], s[38:39]
	s_cbranch_execz .LBB0_305
	s_ashr_i32 s83, s82, 31
	s_lshl_b64 s[30:31], s[82:83], 6
	s_add_u32 s30, s2, s30
	v_mov_b32_e32 v84, s15
	v_mov_b32_e32 v85, s17
	s_addc_u32 s31, s14, s31
	v_pk_add_f32 v[84:85], s[0:1], v[84:85]
	s_nop 0
	v_add_f32_e32 v86, v84, v85
	v_mov_b64_e32 v[84:85], s[30:31]
	global_store_dword v[84:85], v86, off
; __device__ __forceinline__ float bf2f(bf16 b) { return __uint_as_float((unsigned)b << 16); }
; __device__ __forceinline__ bf16 f2bf(float f) { return (bf16)(pk_bf16(f, 0.f) & 0xffffu); }
; __device__ __forceinline__ float fexp(float x) { return __builtin_amdgcn_exp2f(x * 1.4426950408889634f); }
; __device__ __forceinline__ float flog(float x) { return __builtin_amdgcn_logf(x) * 0.6931471805599453f; }
; __device__ __forceinline__ float fsigmoid(float x) { return __builtin_amdgcn_rcpf(1.0f + fexp(-x)); }
; __device__ __forceinline__ void pc_phase(LAS unsigned char* lds, const bf16* Pp_, const bf16* LO, const float* mu, const float* w0, const float* a0, const float* k_k, const float* k_a, const float* r_k, ...
;     ...
;         for (int t = 0; t < 16; ++t) {
;             const float r0 = bf2f(sr_[t + 1]), k0 = bf2f(sk_[t + 1]), v0 = bf2f(sv_[t + 1]);
;             const float r = r0 + (r1 - r0) * mu_r, k = k0 + (k1 - k0) * mu_k, v = v0 + (v1 - v0) * mu_v; r1 = r0; k1 = k0; v1 = v0;
;             const float z = -(w0c + bf2f(slw[t])); const float sp = fmaxf(z, 0.f) + flog(1.0f + fexp(-fabsf(z))); const float w = -sp - 0.5f;
;             const float dec = fexp(-fexp(w)); const float a = fsigmoid(a0c + bf2f(sla[t]));
;             float kk = k * kkc; const float n2 = wsum_dpp(kk * kk); kk = kk / fmaxf(sqrtf(n2), 1e-12f);
;             const float kp = bf2f(f2bf(k * (1.0f + (a - 1.0f) * kac))), bb = bf2f(f2bf(kk * a)), rr = bf2f(f2bf(r)); kk = bf2f(f2bf(kk));
;             const float coef = wsum_dpp(rr * kp * rkc);
;             SV[(ib + t) * 64 + lane] = f2bf(v);
;             if (lane == 0) COEF[(size_t)(m0 + t) * 16 + h] = coef;
;             const float Pp = P; P *= dec; const float inv = 1.0f / P;
;             XKK[t * 72 + lane] = f2bf(kk * Pp); XR[t * 72 + lane] = f2bf(rr * P); XK[t * 72 + lane] = f2bf(kp * inv); XB[t * 72 + lane] = f2bf(bb * inv); }
.LBB0_305:
	s_or_b64 exec, exec, s[4:5]
	v_lshlrev_b32_e32 v75, 16, v75
	v_add_f32_e32 v75, v8, v75
	v_mul_f32_e64 v84, |v75|, s19
	v_exp_f32_e32 v84, v84
	v_mov_b32_e32 v85, s8
	v_mov_b32_e32 v86, s9
	v_add_f32_e32 v85, s7, v85
	v_add_f32_e32 v84, 1.0, v84
	v_log_f32_e32 v84, v84
	v_add_f32_e32 v86, s6, v86
	v_max_f32_e64 v75, -v75, 0
	v_add_f32_e32 v85, v85, v86
	v_fmac_f32_e32 v75, 0x3f317218, v84
	v_mul_f32_e32 v84, 0x4f800000, v85
	v_cmp_gt_f32_e32 vcc, s33, v85
	v_sub_f32_e32 v75, -0.5, v75
	v_mul_f32_e32 v75, 0x3fb8aa3b, v75
	v_cndmask_b32_e32 v84, v85, v84, vcc
	v_sqrt_f32_e32 v85, v84
	v_exp_f32_e32 v75, v75
	v_lshlrev_b32_e32 v71, 16, v71
	v_add_f32_e32 v71, v15, v71
	v_add_u32_e32 v86, -1, v85
	v_fma_f32 v87, -v86, v85, v84
	v_cmp_ge_f32_e64 s[56:57], 0, v87
	v_add_u32_e32 v87, 1, v85
	v_mul_f32_e32 v75, 0xbfb8aa3b, v75
	v_cndmask_b32_e64 v86, v85, v86, s[56:57]
	v_fma_f32 v85, -v87, v85, v84
	v_cmp_lt_f32_e64 s[56:57], 0, v85
	v_exp_f32_e32 v75, v75
	v_mul_f32_e32 v71, 0xbfb8aa3b, v71
	v_cndmask_b32_e64 v85, v86, v87, s[56:57]
	v_mul_f32_e32 v86, 0x37800000, v85
	v_cndmask_b32_e32 v85, v85, v86, vcc
	v_cmp_class_f32_e32 vcc, v84, v219
	v_mul_f32_e32 v75, v80, v75
	v_exp_f32_e32 v71, v71
	v_cndmask_b32_e32 v84, v85, v84, vcc
	v_max_f32_e32 v84, 0x2b8cbccc, v84
	v_div_scale_f32 v85, s[0:1], v84, v84, v83
	v_rcp_f32_e32 v86, v85
	v_mul_f32_e32 v79, v75, v79
	v_lshlrev_b32_e32 v73, 16, v73
	v_sub_f32_e32 v78, v78, v73
	v_fma_f32 v87, -v85, v86, 1.0
	v_fmac_f32_e32 v86, v87, v86
	v_div_scale_f32 v87, vcc, v83, v84, v83
	v_mul_f32_e32 v88, v87, v86
	v_fma_f32 v89, -v85, v88, v87
	v_fmac_f32_e32 v88, v89, v86
	v_fma_f32 v85, -v85, v88, v87
	v_div_fmas_f32 v85, v85, v86, v88
	v_div_fixup_f32 v83, v85, v84, v83
	v_mul_f32_e32 v82, v82, v83
	v_cvt_pk_bf16_f32 v82, v82, s0
	v_div_scale_f32 v84, s[0:1], v75, v75, 1.0
	v_rcp_f32_e32 v85, v84
	v_lshlrev_b32_e32 v82, 16, v82
	v_cvt_pk_bf16_f32 v83, v83, s0
	v_lshlrev_b32_e32 v83, 16, v83
	v_fma_f32 v86, -v84, v85, 1.0
	v_fmac_f32_e32 v85, v86, v85
	v_div_scale_f32 v86, vcc, 1.0, v75, 1.0
	v_mul_f32_e32 v87, v86, v85
	v_fma_f32 v88, -v84, v87, v86
	v_fmac_f32_e32 v87, v88, v85
	v_fma_f32 v84, -v84, v87, v86
	v_div_fmas_f32 v84, v84, v85, v87
	v_div_fixup_f32 v84, v84, v75, 1.0
	v_mul_f32_e32 v76, v84, v76
	v_cvt_pk_bf16_f32 v76, v76, s0
	ds_write_b16 v27, v76 offset:6192
	v_mul_f32_e32 v76, v84, v82
	v_cvt_pk_bf16_f32 v79, v79, s0
	v_cvt_pk_bf16_f32 v76, v76, s0
	v_mul_f32_e32 v80, v80, v83
	ds_write_b16 v27, v79 offset:3888
	ds_write_b16 v27, v76 offset:8496
	v_lshlrev_b32_e32 v76, 16, v72
	v_lshlrev_b32_e32 v72, 16, v74
	v_fma_f32 v79, v9, v78, v73
	v_cvt_pk_bf16_f32 v80, v80, s0
	v_sub_f32_e32 v77, v77, v72
	v_add_f32_e32 v71, 1.0, v71
	v_mul_f32_e32 v78, v14, v79
	ds_write_b16 v27, v80 offset:1584
	v_fma_f32 v80, v12, v77, v72
	v_rcp_f32_e32 v77, v71
	v_mul_f32_e32 v71, v78, v78
	v_sub_f32_e32 v74, v81, v76
	v_fma_f32 v74, v10, v74, v76
	v_mov_b32_dpp v71, v71 quad_perm:[1,0,3,2] row_mask:0xf bank_mask:0xf bound_ctrl:1
	v_fmac_f32_e32 v71, v78, v78
	v_cvt_pk_bf16_f32 v74, v74, s0
	v_lshlrev_b32_e32 v74, 16, v74
	v_add_f32_dpp v71, v71, v71 quad_perm:[2,3,0,1] row_mask:0xf bank_mask:0xf bound_ctrl:1
	s_nop 1
	v_add_f32_dpp v71, v71, v71 row_ror:4 row_mask:0xf bank_mask:0xf bound_ctrl:1
	s_nop 1
	v_add_f32_dpp v71, v71, v71 row_ror:8 row_mask:0xf bank_mask:0xf bound_ctrl:1
	s_nop 0
	v_readlane_b32 s7, v71, 0
	v_readlane_b32 s8, v71, 16
	v_readlane_b32 s6, v71, 32
	v_readlane_b32 s9, v71, 48
	v_add_f32_e32 v71, -1.0, v77
	v_fma_f32 v71, v13, v71, 1.0
	v_mul_f32_e32 v71, v79, v71
	v_cvt_pk_bf16_f32 v71, v71, s0
	v_lshlrev_b32_e32 v71, 16, v71
	v_mul_f32_e32 v79, v74, v71
	v_mul_f32_e32 v81, v11, v79
	s_nop 1
	v_mov_b32_dpp v81, v81 quad_perm:[1,0,3,2] row_mask:0xf bank_mask:0xf bound_ctrl:1
	v_fmac_f32_e32 v81, v11, v79
	s_nop 1
	v_add_f32_dpp v79, v81, v81 quad_perm:[2,3,0,1] row_mask:0xf bank_mask:0xf bound_ctrl:1
	s_nop 1
	v_add_f32_dpp v79, v79, v79 row_ror:4 row_mask:0xf bank_mask:0xf bound_ctrl:1
	s_nop 1
	v_add_f32_dpp v79, v79, v79 row_ror:8 row_mask:0xf bank_mask:0xf bound_ctrl:1
	s_nop 0
	v_readlane_b32 s0, v79, 0
	v_readlane_b32 s15, v79, 16
	v_readlane_b32 s1, v79, 32
	v_readlane_b32 s17, v79, 48
	v_cvt_pk_bf16_f32 v79, v80, s0
	global_store_short v[156:157], v79, off offset:1536
	s_and_saveexec_b64 s[4:5], s[38:39]
	s_cbranch_execz .LBB0_307
	s_ashr_i32 s81, s80, 31
	s_lshl_b64 s[30:31], s[80:81], 6
	s_add_u32 s30, s2, s30
	v_mov_b32_e32 v80, s15
	v_mov_b32_e32 v81, s17
	s_addc_u32 s31, s14, s31
	v_pk_add_f32 v[80:81], s[0:1], v[80:81]
	s_nop 0
	v_add_f32_e32 v79, v80, v81
	v_mov_b64_e32 v[80:81], s[30:31]
	global_store_dword v[80:81], v79, off
; __device__ __forceinline__ float bf2f(bf16 b) { return __uint_as_float((unsigned)b << 16); }
; __device__ __forceinline__ bf16 f2bf(float f) { return (bf16)(pk_bf16(f, 0.f) & 0xffffu); }
; __device__ __forceinline__ float fexp(float x) { return __builtin_amdgcn_exp2f(x * 1.4426950408889634f); }
; __device__ __forceinline__ float flog(float x) { return __builtin_amdgcn_logf(x) * 0.6931471805599453f; }
; __device__ __forceinline__ float fsigmoid(float x) { return __builtin_amdgcn_rcpf(1.0f + fexp(-x)); }
; __device__ __forceinline__ float wsum_dpp(float x) { x = red16(x);
;     return (__builtin_bit_cast(float, __builtin_amdgcn_readlane(__builtin_bit_cast(int, x), 0)) + __builtin_bit_cast(float, __builtin_amdgcn_readlane(__builtin_bit_cast(int, x), 16)))
;          + (__builtin_bit_cast(float, __builtin_amdgcn_readlane(__builtin_bit_cast(int, x), 32)) + __builtin_bit_cast(float, __builtin_amdgcn_readlane(__builtin_bit_cast(int, x), 48))); }
; __device__ __forceinline__ void pc_phase(LAS unsigned char* lds, const bf16* Pp_, const bf16* LO, const float* mu, const float* w0, const float* a0, const float* k_k, const float* k_a, const float* r_k, ...
;     ...
;         for (int t = 0; t < 16; ++t) {
;             const float r0 = bf2f(sr_[t + 1]), k0 = bf2f(sk_[t + 1]), v0 = bf2f(sv_[t + 1]);
;             const float r = r0 + (r1 - r0) * mu_r, k = k0 + (k1 - k0) * mu_k, v = v0 + (v1 - v0) * mu_v; r1 = r0; k1 = k0; v1 = v0;
;             const float z = -(w0c + bf2f(slw[t])); const float sp = fmaxf(z, 0.f) + flog(1.0f + fexp(-fabsf(z))); const float w = -sp - 0.5f;
;             const float dec = fexp(-fexp(w)); const float a = fsigmoid(a0c + bf2f(sla[t]));
;             float kk = k * kkc; const float n2 = wsum_dpp(kk * kk); kk = kk / fmaxf(sqrtf(n2), 1e-12f);
;             const float kp = bf2f(f2bf(k * (1.0f + (a - 1.0f) * kac))), bb = bf2f(f2bf(kk * a)), rr = bf2f(f2bf(r)); kk = bf2f(f2bf(kk));
;             const float coef = wsum_dpp(rr * kp * rkc);
;             SV[(ib + t) * 64 + lane] = f2bf(v);
;             if (lane == 0) COEF[(size_t)(m0 + t) * 16 + h] = coef;
;             const float Pp = P; P *= dec; const float inv = 1.0f / P;
;             XKK[t * 72 + lane] = f2bf(kk * Pp); XR[t * 72 + lane] = f2bf(rr * P); XK[t * 72 + lane] = f2bf(kp * inv); XB[t * 72 + lane] = f2bf(bb * inv); }
.LBB0_307:
	s_or_b64 exec, exec, s[4:5]
	v_lshlrev_b32_e32 v70, 16, v70
	v_add_f32_e32 v70, v8, v70
	v_mul_f32_e64 v79, |v70|, s19
	v_exp_f32_e32 v79, v79
	v_mov_b32_e32 v80, s8
	v_mov_b32_e32 v81, s9
	v_add_f32_e32 v80, s7, v80
	v_add_f32_e32 v79, 1.0, v79
	v_log_f32_e32 v79, v79
	v_add_f32_e32 v81, s6, v81
	v_max_f32_e64 v70, -v70, 0
	v_add_f32_e32 v80, v80, v81
	v_fmac_f32_e32 v70, 0x3f317218, v79
	v_mul_f32_e32 v79, 0x4f800000, v80
	v_cmp_gt_f32_e32 vcc, s33, v80
	v_sub_f32_e32 v70, -0.5, v70
	v_mul_f32_e32 v70, 0x3fb8aa3b, v70
	v_cndmask_b32_e32 v79, v80, v79, vcc
	v_sqrt_f32_e32 v80, v79
	v_exp_f32_e32 v70, v70
	v_lshlrev_b32_e32 v69, 16, v69
	v_add_f32_e32 v69, v15, v69
	v_add_u32_e32 v81, -1, v80
	v_fma_f32 v82, -v81, v80, v79
	v_cmp_ge_f32_e64 s[56:57], 0, v82
	v_add_u32_e32 v82, 1, v80
	v_mul_f32_e32 v70, 0xbfb8aa3b, v70
	v_cndmask_b32_e64 v81, v80, v81, s[56:57]
	v_fma_f32 v80, -v82, v80, v79
	v_cmp_lt_f32_e64 s[56:57], 0, v80
	v_exp_f32_e32 v70, v70
	v_mul_f32_e32 v69, 0xbfb8aa3b, v69
	v_cndmask_b32_e64 v80, v81, v82, s[56:57]
	v_mul_f32_e32 v81, 0x37800000, v80
	v_cndmask_b32_e32 v80, v80, v81, vcc
	v_cmp_class_f32_e32 vcc, v79, v219
	v_mul_f32_e32 v70, v75, v70
	v_mul_f32_e32 v74, v70, v74
	v_cndmask_b32_e32 v79, v80, v79, vcc
	v_max_f32_e32 v79, 0x2b8cbccc, v79
	v_div_scale_f32 v80, s[0:1], v79, v79, v78
	v_rcp_f32_e32 v81, v80
	v_exp_f32_e32 v69, v69
	v_lshlrev_b32_e32 v67, 16, v67
	v_fma_f32 v82, -v80, v81, 1.0
	v_fmac_f32_e32 v81, v82, v81
	v_div_scale_f32 v82, vcc, v78, v79, v78
	v_mul_f32_e32 v83, v82, v81
	v_fma_f32 v84, -v80, v83, v82
	v_fmac_f32_e32 v83, v84, v81
	v_fma_f32 v80, -v80, v83, v82
	v_div_fmas_f32 v80, v80, v81, v83
	v_div_fixup_f32 v78, v80, v79, v78
	v_mul_f32_e32 v77, v77, v78
	v_cvt_pk_bf16_f32 v77, v77, s0
	v_div_scale_f32 v79, s[0:1], v70, v70, 1.0
	v_rcp_f32_e32 v80, v79
	v_lshlrev_b32_e32 v77, 16, v77
	v_cvt_pk_bf16_f32 v78, v78, s0
	v_cvt_pk_bf16_f32 v74, v74, s0
	v_fma_f32 v81, -v79, v80, 1.0
	v_fmac_f32_e32 v80, v81, v80
	v_div_scale_f32 v81, vcc, 1.0, v70, 1.0
	v_mul_f32_e32 v82, v81, v80
	v_fma_f32 v83, -v79, v82, v81
	v_fmac_f32_e32 v82, v83, v80
	v_fma_f32 v79, -v79, v82, v81
	v_div_fmas_f32 v79, v79, v80, v82
	v_div_fixup_f32 v79, v79, v70, 1.0
	v_mul_f32_e32 v71, v79, v71
	v_cvt_pk_bf16_f32 v71, v71, s0
	ds_write_b16 v27, v71 offset:6336
	v_mul_f32_e32 v71, v79, v77
	v_cvt_pk_bf16_f32 v71, v71, s0
	ds_write_b16 v27, v71 offset:8640
	v_lshlrev_b32_e32 v71, 16, v66
	v_lshlrev_b32_e32 v66, 16, v68
	v_sub_f32_e32 v68, v76, v71
	v_lshlrev_b32_e32 v78, 16, v78
	ds_write_b16 v27, v74 offset:4032
	v_fma_f32 v74, v10, v68, v71
	v_sub_f32_e32 v68, v73, v67
	v_mul_f32_e32 v75, v75, v78
	v_fma_f32 v68, v9, v68, v67
	v_cvt_pk_bf16_f32 v75, v75, s0
	v_sub_f32_e32 v72, v72, v66
	v_add_f32_e32 v69, 1.0, v69
	v_mul_f32_e32 v73, v14, v68
	ds_write_b16 v27, v75 offset:1728
	v_fma_f32 v75, v12, v72, v66
	v_rcp_f32_e32 v72, v69
	v_mul_f32_e32 v69, v73, v73
	s_nop 1
	v_mov_b32_dpp v69, v69 quad_perm:[1,0,3,2] row_mask:0xf bank_mask:0xf bound_ctrl:1
	v_fmac_f32_e32 v69, v73, v73
	s_nop 1
	v_add_f32_dpp v69, v69, v69 quad_perm:[2,3,0,1] row_mask:0xf bank_mask:0xf bound_ctrl:1
	s_nop 1
	v_add_f32_dpp v69, v69, v69 row_ror:4 row_mask:0xf bank_mask:0xf bound_ctrl:1
	s_nop 1
	v_add_f32_dpp v69, v69, v69 row_ror:8 row_mask:0xf bank_mask:0xf bound_ctrl:1
	s_nop 0
	v_readlane_b32 s7, v69, 0
	v_readlane_b32 s8, v69, 16
	v_readlane_b32 s6, v69, 32
	v_readlane_b32 s9, v69, 48
	v_add_f32_e32 v69, -1.0, v72
	v_fma_f32 v69, v13, v69, 1.0
	v_mul_f32_e32 v68, v68, v69
	v_cvt_pk_bf16_f32 v68, v68, s0
	v_cvt_pk_bf16_f32 v69, v74, s0
	v_lshlrev_b32_e32 v68, 16, v68
	v_lshlrev_b32_e32 v69, 16, v69
	v_mul_f32_e32 v74, v69, v68
	v_mul_f32_e32 v76, v11, v74
	s_nop 1
	v_mov_b32_dpp v76, v76 quad_perm:[1,0,3,2] row_mask:0xf bank_mask:0xf bound_ctrl:1
	v_fmac_f32_e32 v76, v11, v74
	s_nop 1
	v_add_f32_dpp v74, v76, v76 quad_perm:[2,3,0,1] row_mask:0xf bank_mask:0xf bound_ctrl:1
	s_nop 1
	v_add_f32_dpp v74, v74, v74 row_ror:4 row_mask:0xf bank_mask:0xf bound_ctrl:1
	s_nop 1
	v_add_f32_dpp v74, v74, v74 row_ror:8 row_mask:0xf bank_mask:0xf bound_ctrl:1
	s_nop 0
	v_readlane_b32 s0, v74, 0
	v_readlane_b32 s15, v74, 16
	v_readlane_b32 s1, v74, 32
	v_readlane_b32 s17, v74, 48
	v_cvt_pk_bf16_f32 v76, v75, s0
	global_store_short v[156:157], v76, off offset:1664
	s_and_saveexec_b64 s[4:5], s[38:39]
	s_cbranch_execz .LBB0_309
	s_mov_b32 s34, s79
	s_ashr_i32 s79, s78, 31
	s_lshl_b64 s[30:31], s[78:79], 6
	s_add_u32 s30, s2, s30
	v_mov_b32_e32 v74, s15
	v_mov_b32_e32 v75, s17
	s_addc_u32 s31, s14, s31
	v_pk_add_f32 v[74:75], s[0:1], v[74:75]
	s_mov_b32 s79, s34
	v_add_f32_e32 v76, v74, v75
	v_mov_b64_e32 v[74:75], s[30:31]
	global_store_dword v[74:75], v76, off
; __device__ __forceinline__ float bf2f(bf16 b) { return __uint_as_float((unsigned)b << 16); }
; __device__ __forceinline__ bf16 f2bf(float f) { return (bf16)(pk_bf16(f, 0.f) & 0xffffu); }
; __device__ __forceinline__ float fexp(float x) { return __builtin_amdgcn_exp2f(x * 1.4426950408889634f); }
; __device__ __forceinline__ float flog(float x) { return __builtin_amdgcn_logf(x) * 0.6931471805599453f; }
; __device__ __forceinline__ float fsigmoid(float x) { return __builtin_amdgcn_rcpf(1.0f + fexp(-x)); }
; __device__ __forceinline__ float wsum_dpp(float x) { x = red16(x);
;     return (__builtin_bit_cast(float, __builtin_amdgcn_readlane(__builtin_bit_cast(int, x), 0)) + __builtin_bit_cast(float, __builtin_amdgcn_readlane(__builtin_bit_cast(int, x), 16)))
;          + (__builtin_bit_cast(float, __builtin_amdgcn_readlane(__builtin_bit_cast(int, x), 32)) + __builtin_bit_cast(float, __builtin_amdgcn_readlane(__builtin_bit_cast(int, x), 48))); }
; __device__ __forceinline__ void pc_phase(LAS unsigned char* lds, const bf16* Pp_, const bf16* LO, const float* mu, const float* w0, const float* a0, const float* k_k, const float* k_a, const float* r_k, ...
;     ...
;         for (int t = 0; t < 16; ++t) {
;             const float r0 = bf2f(sr_[t + 1]), k0 = bf2f(sk_[t + 1]), v0 = bf2f(sv_[t + 1]);
;             const float r = r0 + (r1 - r0) * mu_r, k = k0 + (k1 - k0) * mu_k, v = v0 + (v1 - v0) * mu_v; r1 = r0; k1 = k0; v1 = v0;
;             const float z = -(w0c + bf2f(slw[t])); const float sp = fmaxf(z, 0.f) + flog(1.0f + fexp(-fabsf(z))); const float w = -sp - 0.5f;
;             const float dec = fexp(-fexp(w)); const float a = fsigmoid(a0c + bf2f(sla[t]));
;             float kk = k * kkc; const float n2 = wsum_dpp(kk * kk); kk = kk / fmaxf(sqrtf(n2), 1e-12f);
;             const float kp = bf2f(f2bf(k * (1.0f + (a - 1.0f) * kac))), bb = bf2f(f2bf(kk * a)), rr = bf2f(f2bf(r)); kk = bf2f(f2bf(kk));
;             const float coef = wsum_dpp(rr * kp * rkc);
;             SV[(ib + t) * 64 + lane] = f2bf(v);
;             if (lane == 0) COEF[(size_t)(m0 + t) * 16 + h] = coef;
;             const float Pp = P; P *= dec; const float inv = 1.0f / P;
;             XKK[t * 72 + lane] = f2bf(kk * Pp); XR[t * 72 + lane] = f2bf(rr * P); XK[t * 72 + lane] = f2bf(kp * inv); XB[t * 72 + lane] = f2bf(bb * inv); }
.LBB0_309:
	s_or_b64 exec, exec, s[4:5]
	v_lshlrev_b32_e32 v65, 16, v65
	v_add_f32_e32 v65, v8, v65
	v_mul_f32_e64 v74, |v65|, s19
	v_exp_f32_e32 v74, v74
	v_mov_b32_e32 v75, s8
	v_mov_b32_e32 v76, s9
	v_add_f32_e32 v75, s7, v75
	v_add_f32_e32 v74, 1.0, v74
	v_log_f32_e32 v74, v74
	v_add_f32_e32 v76, s6, v76
	v_max_f32_e64 v65, -v65, 0
	v_add_f32_e32 v75, v75, v76
	v_fmac_f32_e32 v65, 0x3f317218, v74
	v_mul_f32_e32 v74, 0x4f800000, v75
	v_cmp_gt_f32_e32 vcc, s33, v75
	v_sub_f32_e32 v65, -0.5, v65
	v_mul_f32_e32 v65, 0x3fb8aa3b, v65
	v_cndmask_b32_e32 v74, v75, v74, vcc
	v_sqrt_f32_e32 v75, v74
	v_exp_f32_e32 v65, v65
	v_lshlrev_b32_e32 v61, 16, v61
	v_add_f32_e32 v61, v15, v61
	v_add_u32_e32 v76, -1, v75
	v_fma_f32 v77, -v76, v75, v74
	v_cmp_ge_f32_e64 s[56:57], 0, v77
	v_add_u32_e32 v77, 1, v75
	v_mul_f32_e32 v65, 0xbfb8aa3b, v65
	v_cndmask_b32_e64 v76, v75, v76, s[56:57]
	v_fma_f32 v75, -v77, v75, v74
	v_cmp_lt_f32_e64 s[56:57], 0, v75
	v_exp_f32_e32 v65, v65
	v_mul_f32_e32 v61, 0xbfb8aa3b, v61
	v_cndmask_b32_e64 v75, v76, v77, s[56:57]
	v_mul_f32_e32 v76, 0x37800000, v75
	v_cndmask_b32_e32 v75, v75, v76, vcc
	v_cmp_class_f32_e32 vcc, v74, v219
	v_mul_f32_e32 v65, v70, v65
	v_exp_f32_e32 v61, v61
	v_cndmask_b32_e32 v74, v75, v74, vcc
	v_max_f32_e32 v74, 0x2b8cbccc, v74
	v_div_scale_f32 v75, s[0:1], v74, v74, v73
	v_rcp_f32_e32 v76, v75
	v_mul_f32_e32 v69, v65, v69
	v_lshlrev_b32_e32 v63, 16, v63
	v_sub_f32_e32 v67, v67, v63
	v_fma_f32 v77, -v75, v76, 1.0
	v_fmac_f32_e32 v76, v77, v76
	v_div_scale_f32 v77, vcc, v73, v74, v73
	v_mul_f32_e32 v78, v77, v76
	v_fma_f32 v79, -v75, v78, v77
	v_fmac_f32_e32 v78, v79, v76
	v_fma_f32 v75, -v75, v78, v77
	v_div_fmas_f32 v75, v75, v76, v78
	v_div_fixup_f32 v73, v75, v74, v73
	v_mul_f32_e32 v72, v72, v73
	v_cvt_pk_bf16_f32 v72, v72, s0
	v_div_scale_f32 v74, s[0:1], v65, v65, 1.0
	v_rcp_f32_e32 v75, v74
	v_lshlrev_b32_e32 v72, 16, v72
	v_cvt_pk_bf16_f32 v73, v73, s0
	v_lshlrev_b32_e32 v73, 16, v73
	v_fma_f32 v76, -v74, v75, 1.0
	v_fmac_f32_e32 v75, v76, v75
	v_div_scale_f32 v76, vcc, 1.0, v65, 1.0
	v_mul_f32_e32 v77, v76, v75
	v_fma_f32 v78, -v74, v77, v76
	v_fmac_f32_e32 v77, v78, v75
	v_fma_f32 v74, -v74, v77, v76
	v_div_fmas_f32 v74, v74, v75, v77
	v_div_fixup_f32 v74, v74, v65, 1.0
	v_mul_f32_e32 v68, v74, v68
	v_cvt_pk_bf16_f32 v68, v68, s0
	ds_write_b16 v27, v68 offset:6480
	v_mul_f32_e32 v68, v74, v72
	v_cvt_pk_bf16_f32 v69, v69, s0
	v_cvt_pk_bf16_f32 v68, v68, s0
	v_mul_f32_e32 v70, v70, v73
	ds_write_b16 v27, v69 offset:4176
	ds_write_b16 v27, v68 offset:8784
	v_lshlrev_b32_e32 v68, 16, v62
	v_lshlrev_b32_e32 v62, 16, v64
	v_fma_f32 v69, v9, v67, v63
	v_cvt_pk_bf16_f32 v70, v70, s0
	v_sub_f32_e32 v66, v66, v62
	v_add_f32_e32 v61, 1.0, v61
	v_mul_f32_e32 v67, v14, v69
	ds_write_b16 v27, v70 offset:1872
	v_fma_f32 v70, v12, v66, v62
	v_rcp_f32_e32 v66, v61
	v_mul_f32_e32 v61, v67, v67
	v_sub_f32_e32 v64, v71, v68
	v_fma_f32 v64, v10, v64, v68
	v_mov_b32_dpp v61, v61 quad_perm:[1,0,3,2] row_mask:0xf bank_mask:0xf bound_ctrl:1
	v_fmac_f32_e32 v61, v67, v67
	v_cvt_pk_bf16_f32 v64, v64, s0
	v_lshlrev_b32_e32 v64, 16, v64
	v_add_f32_dpp v61, v61, v61 quad_perm:[2,3,0,1] row_mask:0xf bank_mask:0xf bound_ctrl:1
	s_nop 1
	v_add_f32_dpp v61, v61, v61 row_ror:4 row_mask:0xf bank_mask:0xf bound_ctrl:1
	s_nop 1
	v_add_f32_dpp v61, v61, v61 row_ror:8 row_mask:0xf bank_mask:0xf bound_ctrl:1
	s_nop 0
	v_readlane_b32 s7, v61, 0
	v_readlane_b32 s8, v61, 16
	v_readlane_b32 s6, v61, 32
	v_readlane_b32 s9, v61, 48
	v_add_f32_e32 v61, -1.0, v66
	v_fma_f32 v61, v13, v61, 1.0
	v_mul_f32_e32 v61, v69, v61
	v_cvt_pk_bf16_f32 v61, v61, s0
	v_lshlrev_b32_e32 v61, 16, v61
	v_mul_f32_e32 v69, v64, v61
	v_mul_f32_e32 v71, v11, v69
	s_nop 1
	v_mov_b32_dpp v71, v71 quad_perm:[1,0,3,2] row_mask:0xf bank_mask:0xf bound_ctrl:1
	v_fmac_f32_e32 v71, v11, v69
	s_nop 1
	v_add_f32_dpp v69, v71, v71 quad_perm:[2,3,0,1] row_mask:0xf bank_mask:0xf bound_ctrl:1
	s_nop 1
	v_add_f32_dpp v69, v69, v69 row_ror:4 row_mask:0xf bank_mask:0xf bound_ctrl:1
	s_nop 1
	v_add_f32_dpp v69, v69, v69 row_ror:8 row_mask:0xf bank_mask:0xf bound_ctrl:1
	s_nop 0
	v_readlane_b32 s0, v69, 0
	v_readlane_b32 s15, v69, 16
	v_readlane_b32 s1, v69, 32
	v_readlane_b32 s17, v69, 48
	v_cvt_pk_bf16_f32 v69, v70, s0
	global_store_short v[156:157], v69, off offset:1792
	s_and_saveexec_b64 s[4:5], s[38:39]
	s_cbranch_execz .LBB0_311
	s_ashr_i32 s77, s76, 31
	s_lshl_b64 s[30:31], s[76:77], 6
	s_add_u32 s30, s2, s30
	v_mov_b32_e32 v70, s15
	v_mov_b32_e32 v71, s17
	s_addc_u32 s31, s14, s31
	v_pk_add_f32 v[70:71], s[0:1], v[70:71]
	v_readlane_b32 s77, v254, 56
	v_add_f32_e32 v69, v70, v71
	v_mov_b64_e32 v[70:71], s[30:31]
	global_store_dword v[70:71], v69, off
